# retention-output and spatial-gating unit epilogues: per-group gate/gain/u loads issued early into free registers (ret: one wait, drains removed; sgu: waits kept); on top of norm_rows gain hoist
# speedup vs baseline: 1.0157x; 1.0037x over previous
; #define LAS __attribute__((address_space(3)))
; __device__ __forceinline__ unsigned pk2(float lo, float hi) { return pg8::cvt_pk_bf16(lo, hi); }
; __device__ __forceinline__ float fexp2(float x) { return __builtin_amdgcn_exp2f(x); }
; __device__ __forceinline__ float ret_log2gamma(int h) { return log2f(1.f - exp2f(-5.f - (float)h)); }
; __device__ __forceinline__ void stage_nat(LAS bfu* dst, const bfu* src, int pitch, int tid) {
; #pragma unroll
;     for (int i = 0; i < 4; ++i) { const int id = tid + NTHR * i, r = id >> 4, ch = id & 15; const v4u v = *(const v4u*)(src + (size_t)r * pitch + ch * 8); *(LAS v4u*)(dst + r * TS + ch * 8) = v; }
; }
; template <bool SC> __device__ __forceinline__ void stage_tr(LAS bfu* dst, const bfu* src, int pitch, int tid, float lg) {
; #pragma unroll
;     for (int i = 0; i < 4; ++i) { const int id = tid + NTHR * i, c = id & 127, ch = id >> 7; const v4u v = *(const v4u*)(src + (size_t)c * pitch + ch * 8);
;         const float sc = SC ? fexp2(lg * (float)(127 - c)) : 1.f;
; #pragma unroll
;         for (int j = 0; j < 4; ++j) { unsigned w = v[j];
;             if (SC) w = pk2(bflo(w) * sc, bfhi(w) * sc);
;             dst[(ch * 8 + 2 * j) * TS + c] = (bfu)(w & 0xffffu); dst[(ch * 8 + 2 * j + 1) * TS + c] = (bfu)(w >> 16); } }
; __device__ __forceinline__ void ret_unit(LAS unsigned char* lds, const bfu* PROJ, const bfu* RT, const float* gn_g, bfu* CAT, int u) {
;     int tid = threadIdx.x; asm volatile("" : "+v"(tid)); const int lane = tid & 63, wid = __builtin_amdgcn_readfirstlane(tid >> 6); (void)lane; (void)wid;
;     const int bh = u >> 6, i = u & 63, b = bh / 6, h = bh % 6; const size_t row0 = (size_t)b * SEQ + (size_t)i * 128; const float lg = ret_log2gamma(h);
;     LAS bfu* Qs = (LAS bfu*)lds; LAS bfu* Ks = (LAS bfu*)(lds + TILE_B); LAS bfu* Vt = (LAS bfu*)(lds + 2 * TILE_B); LAS bfu* Rt = (LAS bfu*)(lds + 3 * TILE_B);
;     const bfu* P0 = PROJ + row0 * INW + h * 128;
;     stage_nat(Qs, P0 + C_RQ, INW, tid); stage_nat(Ks, P0 + C_RK, INW, tid); stage_tr<false>(Vt, P0 + C_RV, INW, tid, 0.f); stage_nat(Rt, RT + (size_t)u * 16384, 128, tid);
.LBB0_410:
	s_or_b64 exec, exec, s[40:41]
	s_mov_b32 s22, 21
	s_barrier
	s_ashr_i32 s23, s22, 31
	s_lshl_b64 s[22:23], s[22:23], 3
	s_add_u32 s22, s0, s22
	s_addc_u32 s23, s1, s23
	s_load_dwordx2 s[48:49], s[22:23], 0x0
	s_mov_b32 s22, 21
	s_ashr_i32 s23, s22, 31
	s_lshl_b64 s[22:23], s[22:23], 3
	s_add_u32 s22, s0, s22
	s_addc_u32 s23, s1, s23
	s_load_dwordx2 s[40:41], s[22:23], 0x0
	s_mov_b32 s22, 3
	s_ashr_i32 s23, s22, 31
	s_lshl_b64 s[22:23], s[22:23], 3
	s_add_u32 s22, s0, s22
	s_addc_u32 s23, s1, s23
	s_load_dwordx2 s[22:23], s[22:23], 0x0
	v_mov_b32_e32 v10, v232
	v_readlane_b32 s91, v255, 54
	s_waitcnt lgkmcnt(0)
	s_add_u32 s20, s22, s36
	s_mov_b32 s22, 21
	s_addc_u32 s35, s23, s37
	s_ashr_i32 s23, s22, 31
	s_lshl_b64 s[22:23], s[22:23], 3
	s_add_u32 s22, s0, s22
	s_addc_u32 s23, s1, s23
	s_load_dwordx2 s[44:45], s[22:23], 0x0
	s_mul_hi_i32 s23, s34, 0x2aaaaaab
	s_lshr_b32 s46, s23, 31
	s_add_i32 s46, s23, s46
	s_mul_i32 s23, s46, 6
	s_sub_i32 s23, s34, s23
	v_cvt_f32_i32_e32 v0, s23
	s_ashr_i32 s47, s46, 31
	s_lshl_b32 s34, s92, 7
	s_lshl_b64 s[46:47], s[46:47], 13
	v_sub_f32_e32 v0, 0xc0a00000, v0
	v_cmp_gt_f32_e32 vcc, s64, v0
	s_and_b32 s34, s34, 0x1f80
	s_or_b32 s46, s46, s34
	v_cndmask_b32_e32 v2, 0, v241, vcc
	v_add_f32_e32 v0, v0, v2
	v_exp_f32_e32 v0, v0
	s_and_b64 s[50:51], vcc, exec
	s_cselect_b32 s34, 0xffffffc0, 0
	s_mul_hi_u32 s50, s46, 0x3200
	v_ldexp_f32 v0, v0, s34
	s_mul_i32 s34, s47, 0x3200
	s_add_i32 s50, s50, s34
	s_mul_i32 s34, s46, 0x3200
	s_add_u32 s34, s48, s34
	s_addc_u32 s48, s49, s50
	s_lshl_b32 s50, s23, 7
	s_ashr_i32 s51, s50, 31
	s_lshl_b64 s[52:53], s[50:51], 1
	s_add_u32 s23, s34, s52
	s_addc_u32 s34, s48, s53
	v_sub_f32_e32 v11, 1.0, v0
	s_add_u32 s56, s23, 0x1ce00000
	v_lshlrev_b32_e32 v0, 4, v10
	s_addc_u32 s57, s34, 0
	v_and_b32_e32 v0, 0xf0, v0
	v_lshl_add_u64 v[16:17], s[56:57], 0, v[0:1]
	v_ashrrev_i32_e32 v2, 4, v10
	v_mad_i64_i32 v[18:19], s[48:49], v2, s61, v[16:17]
	global_load_dwordx4 v[4:7], v[18:19], off
	v_add_u32_e32 v26, 0, v0
	v_mul_lo_u32 v27, v2, s65
	v_add_u32_e32 v28, v26, v27
	s_ashr_i32 s93, s92, 31
	v_ashrrev_i32_e32 v3, 31, v2
	v_readfirstlane_b32 s22, v10
	v_bfe_u32 v71, v10, 4, 2
	v_lshlrev_b32_e32 v69, 4, v71
	s_waitcnt vmcnt(0)
	ds_write_b128 v28, v[4:7]
	v_add_u32_e32 v4, 0x200, v10
	v_ashrrev_i32_e32 v4, 4, v4
	v_mad_i64_i32 v[20:21], s[48:49], v4, s61, v[16:17]
	global_load_dwordx4 v[6:9], v[20:21], off
	v_mul_lo_u32 v29, v4, s65
	v_add_u32_e32 v30, v26, v29
	v_ashrrev_i32_e32 v5, 31, v4
	s_waitcnt vmcnt(0)
	ds_write_b128 v30, v[6:9]
	v_add_u32_e32 v6, 0x400, v10
	v_ashrrev_i32_e32 v6, 4, v6
	v_mad_i64_i32 v[22:23], s[48:49], v6, s61, v[16:17]
	global_load_dwordx4 v[12:15], v[22:23], off
	v_add_u32_e32 v8, 0x600, v10
	v_mul_lo_u32 v31, v6, s65
	v_ashrrev_i32_e32 v8, 4, v8
	v_add_u32_e32 v32, v26, v31
	v_mad_i64_i32 v[24:25], s[48:49], v8, s61, v[16:17]
	s_lshl_b64 s[48:49], s[92:93], 15
	s_add_u32 s40, s40, s48
	s_addc_u32 s41, s41, s49
	v_ashrrev_i32_e32 v7, 31, v6
	v_ashrrev_i32_e32 v9, 31, v8
	s_ashr_i32 s34, s22, 2
	s_mov_b32 s22, 0x800000
	v_cmp_gt_f32_e32 vcc, s22, v11
	s_and_b64 s[22:23], vcc, exec
	s_cselect_b32 s22, 32, 0
	v_bfi_b32 v66, -16, s34, v10
	s_waitcnt vmcnt(0)
	ds_write_b128 v32, v[12:15]
	global_load_dwordx4 v[14:17], v[24:25], off
	v_mul_lo_u32 v12, v8, s65
	v_add_u32_e32 v13, v26, v12
	s_waitcnt vmcnt(0)
	ds_write_b128 v13, v[14:17]
	global_load_dwordx4 v[14:17], v[18:19], off offset:1536
	s_waitcnt vmcnt(0)
	ds_write_b128 v28, v[14:17] offset:34816
	global_load_dwordx4 v[14:17], v[20:21], off offset:1536
	s_waitcnt vmcnt(0)
	ds_write_b128 v30, v[14:17] offset:34816
	global_load_dwordx4 v[14:17], v[22:23], off offset:1536
	s_waitcnt vmcnt(0)
	ds_write_b128 v32, v[14:17] offset:34816
	global_load_dwordx4 v[14:17], v[24:25], off offset:1536
	s_waitcnt vmcnt(0)
	ds_write_b128 v13, v[14:17] offset:34816
	v_and_b32_e32 v13, 0x7f, v10
	v_mul_u32_u24_e32 v14, 0x1900, v13
	v_lshlrev_b32_e32 v14, 1, v14
	v_mov_b32_e32 v15, v1
	v_lshl_add_u64 v[18:19], s[56:57], 0, v[14:15]
	v_and_b32_e32 v14, -8, v2
	v_ashrrev_i32_e32 v15, 31, v14
	v_lshl_add_u64 v[16:17], v[14:15], 1, v[18:19]
	v_mul_lo_u32 v14, v14, s65
	v_lshlrev_b32_e32 v13, 1, v13
	v_add3_u32 v20, s70, v14, v13
	global_load_dwordx4 v[14:17], v[16:17], off offset:3072
	v_lshlrev_b64 v[2:3], 8, v[2:3]
	s_waitcnt vmcnt(0)
	ds_write_b16 v20, v14
	ds_write_b16_d16_hi v20, v14 offset:272
	ds_write_b16 v20, v15 offset:544
	ds_write_b16_d16_hi v20, v15 offset:816
	ds_write_b16 v20, v16 offset:1088
	ds_write_b16_d16_hi v20, v16 offset:1360
	ds_write_b16 v20, v17 offset:1632
	ds_write_b16_d16_hi v20, v17 offset:1904
	v_and_b32_e32 v14, -8, v4
	v_ashrrev_i32_e32 v15, 31, v14
	v_lshl_add_u64 v[16:17], v[14:15], 1, v[18:19]
	v_mul_lo_u32 v14, v14, s65
	v_add3_u32 v20, s70, v14, v13
	global_load_dwordx4 v[14:17], v[16:17], off offset:3072
	s_waitcnt vmcnt(0)
	ds_write_b16 v20, v14
	ds_write_b16_d16_hi v20, v14 offset:272
	ds_write_b16 v20, v15 offset:544
	ds_write_b16_d16_hi v20, v15 offset:816
	ds_write_b16 v20, v16 offset:1088
	ds_write_b16_d16_hi v20, v16 offset:1360
	ds_write_b16 v20, v17 offset:1632
	ds_write_b16_d16_hi v20, v17 offset:1904
	v_and_b32_e32 v14, -8, v6
	v_ashrrev_i32_e32 v15, 31, v14
	v_lshl_add_u64 v[16:17], v[14:15], 1, v[18:19]
	v_mul_lo_u32 v14, v14, s65
	v_add3_u32 v20, s70, v14, v13
	global_load_dwordx4 v[14:17], v[16:17], off offset:3072
	s_waitcnt vmcnt(0)
; #define LAS __attribute__((address_space(3)))
; #define ZERO8(a) do { _Pragma("unroll") for (int t_ = 0; t_ < 8; ++t_) a[t_] = (f32x4){0.f, 0.f, 0.f, 0.f}; } while (0)
; __device__ __forceinline__ void wave_mma(f32x4 (&acc)[8], const LAS bfu* As, const LAS bfu* Bs, int m0, int fr, int fq) {
; #pragma unroll
;     for (int ks = 0; ks < 4; ++ks) { const bf16x8 a = *(const LAS bf16x8*)(As + (m0 + fr) * TS + ks * 32 + fq * 8);
; #pragma unroll
;         for (int t = 0; t < 8; ++t) { const bf16x8 b = *(const LAS bf16x8*)(Bs + (t * 16 + fr) * TS + ks * 32 + fq * 8); acc[t] = __builtin_amdgcn_mfma_f32_16x16x32_bf16(b, a, acc[t], 0, 0, 0); } }
; }
; __device__ __forceinline__ void ret_unit(LAS unsigned char* lds, const bfu* PROJ, const bfu* RT, const float* gn_g, bfu* CAT, int u) {
;     ...
;     stage_nat(Qs, P0 + C_RQ, INW, tid); stage_nat(Ks, P0 + C_RK, INW, tid); stage_tr<false>(Vt, P0 + C_RV, INW, tid, 0.f); stage_nat(Rt, RT + (size_t)u * 16384, 128, tid);
;     __syncthreads();
;     const int fr = lane & 15, fq = lane >> 4, m0 = wid * 16, c = m0 + fr;
;     f32x4 acc[8], cr[8]; ZERO8(acc); ZERO8(cr);
;     wave_mma(cr, Qs, Rt, m0, fr, fq);
;     wave_mma(acc, Qs, Ks, m0, fr, fq);
	ds_write_b16 v20, v14
	ds_write_b16_d16_hi v20, v14 offset:272
	ds_write_b16 v20, v15 offset:544
	ds_write_b16_d16_hi v20, v15 offset:816
	ds_write_b16 v20, v16 offset:1088
	ds_write_b16_d16_hi v20, v16 offset:1360
	ds_write_b16 v20, v17 offset:1632
	ds_write_b16_d16_hi v20, v17 offset:1904
	v_and_b32_e32 v14, -8, v8
	v_ashrrev_i32_e32 v15, 31, v14
	v_lshl_add_u64 v[16:17], v[14:15], 1, v[18:19]
	v_mul_lo_u32 v14, v14, s65
	v_add3_u32 v13, s70, v14, v13
	global_load_dwordx4 v[14:17], v[16:17], off offset:3072
	s_waitcnt vmcnt(0)
	ds_write_b16 v13, v14
	ds_write_b16_d16_hi v13, v14 offset:272
	ds_write_b16 v13, v15 offset:544
	ds_write_b16_d16_hi v13, v15 offset:816
	ds_write_b16 v13, v16 offset:1088
	ds_write_b16_d16_hi v13, v16 offset:1360
	ds_write_b16 v13, v17 offset:1632
	ds_write_b16_d16_hi v13, v17 offset:1904
	v_lshl_add_u64 v[14:15], s[40:41], 0, v[0:1]
	s_mov_b64 s[40:41], 0x33600000
	v_lshl_add_u64 v[18:19], v[14:15], 0, s[40:41]
	v_lshl_add_u64 v[2:3], v[18:19], 0, v[2:3]
	global_load_dwordx4 v[14:17], v[2:3], off
	v_readlane_b32 s40, v255, 29
	s_nop 1
	v_add_u32_e32 v0, s40, v0
	v_add_u32_e32 v2, v0, v27
	v_add_u32_e32 v13, v0, v29
	s_waitcnt vmcnt(0)
	ds_write_b128 v2, v[14:17]
	v_lshlrev_b64 v[2:3], 8, v[4:5]
	v_lshl_add_u64 v[2:3], v[18:19], 0, v[2:3]
	global_load_dwordx4 v[2:5], v[2:3], off
	s_waitcnt vmcnt(0)
	ds_write_b128 v13, v[2:5]
	v_lshlrev_b64 v[2:3], 8, v[6:7]
	v_lshl_add_u64 v[2:3], v[18:19], 0, v[2:3]
	global_load_dwordx4 v[2:5], v[2:3], off
	v_add_u32_e32 v6, v0, v31
	v_add_u32_e32 v0, v0, v12
	s_waitcnt vmcnt(0)
	ds_write_b128 v6, v[2:5]
	v_lshlrev_b64 v[2:3], 8, v[8:9]
	v_lshl_add_u64 v[2:3], v[18:19], 0, v[2:3]
	global_load_dwordx4 v[2:5], v[2:3], off
	s_waitcnt vmcnt(0)
	ds_write_b128 v0, v[2:5]
	v_ldexp_f32 v0, v11, s22
	v_log_f32_e32 v0, v0
	v_cndmask_b32_e32 v2, 0, v242, vcc
	s_waitcnt lgkmcnt(0)
	s_barrier
	v_sub_f32_e32 v67, v0, v2
	v_and_b32_e32 v2, 15, v10
	v_mul_lo_u32 v0, v66, s65
	v_add_u32_e32 v73, 0, v0
	v_mul_u32_u24_e32 v70, 0x110, v2
	v_add_u32_e32 v62, v73, v69
	v_add3_u32 v63, s40, v69, v70
	ds_read_b128 v[46:49], v62
	ds_read_b128 v[2:5], v63
	ds_read_b128 v[6:9], v63 offset:4352
	ds_read_b128 v[10:13], v63 offset:8704
	ds_read_b128 v[14:17], v63 offset:13056
	ds_read_b128 v[18:21], v63 offset:17408
	ds_read_b128 v[22:25], v63 offset:21760
	ds_read_b128 v[26:29], v63 offset:26112
	ds_read_b128 v[30:33], v63 offset:30464
	ds_read_b128 v[38:41], v62 offset:64
	ds_read_b128 v[34:37], v63 offset:64
	s_waitcnt lgkmcnt(9)
	v_mfma_f32_16x16x32_bf16 v[2:5], v[2:5], v[46:49], 0
	v_add3_u32 v72, 0, v69, v70
	v_lshlrev_b32_e32 v0, 3, v71
	s_waitcnt lgkmcnt(0)
	v_mfma_f32_16x16x32_bf16 v[2:5], v[34:37], v[38:41], v[2:5]
	ds_read_b128 v[34:37], v63 offset:4416
	v_mfma_f32_16x16x32_bf16 v[6:9], v[6:9], v[46:49], 0
	s_waitcnt lgkmcnt(0)
	v_mfma_f32_16x16x32_bf16 v[6:9], v[34:37], v[38:41], v[6:9]
	ds_read_b128 v[34:37], v63 offset:8768
	v_mfma_f32_16x16x32_bf16 v[10:13], v[10:13], v[46:49], 0
	s_waitcnt lgkmcnt(0)
	v_mfma_f32_16x16x32_bf16 v[10:13], v[34:37], v[38:41], v[10:13]
	ds_read_b128 v[34:37], v63 offset:13120
	v_mfma_f32_16x16x32_bf16 v[14:17], v[14:17], v[46:49], 0
	s_waitcnt lgkmcnt(0)
	v_mfma_f32_16x16x32_bf16 v[14:17], v[34:37], v[38:41], v[14:17]
	ds_read_b128 v[34:37], v63 offset:17472
	v_mfma_f32_16x16x32_bf16 v[18:21], v[18:21], v[46:49], 0
	s_waitcnt lgkmcnt(0)
	v_mfma_f32_16x16x32_bf16 v[18:21], v[34:37], v[38:41], v[18:21]
	ds_read_b128 v[34:37], v63 offset:21824
	v_mfma_f32_16x16x32_bf16 v[22:25], v[22:25], v[46:49], 0
	s_waitcnt lgkmcnt(0)
	v_mfma_f32_16x16x32_bf16 v[22:25], v[34:37], v[38:41], v[22:25]
	ds_read_b128 v[34:37], v63 offset:26176
	v_mfma_f32_16x16x32_bf16 v[26:29], v[26:29], v[46:49], 0
	s_waitcnt lgkmcnt(0)
	v_mfma_f32_16x16x32_bf16 v[26:29], v[34:37], v[38:41], v[26:29]
	ds_read_b128 v[34:37], v63 offset:30528
	v_mfma_f32_16x16x32_bf16 v[30:33], v[30:33], v[46:49], 0
	s_waitcnt lgkmcnt(0)
	v_mfma_f32_16x16x32_bf16 v[30:33], v[34:37], v[38:41], v[30:33]
	ds_read_b128 v[42:45], v62 offset:128
	ds_read_b128 v[34:37], v63 offset:128
	s_waitcnt lgkmcnt(0)
	v_mfma_f32_16x16x32_bf16 v[2:5], v[34:37], v[42:45], v[2:5]
	ds_read_b128 v[34:37], v63 offset:4480
	s_waitcnt lgkmcnt(0)
	v_mfma_f32_16x16x32_bf16 v[6:9], v[34:37], v[42:45], v[6:9]
	ds_read_b128 v[34:37], v63 offset:8832
	s_waitcnt lgkmcnt(0)
	v_mfma_f32_16x16x32_bf16 v[50:53], v[34:37], v[42:45], v[10:13]
	s_nop 2
	ds_read_b128 v[10:13], v63 offset:13184
	s_waitcnt lgkmcnt(0)
	v_mfma_f32_16x16x32_bf16 v[14:17], v[10:13], v[42:45], v[14:17]
	ds_read_b128 v[10:13], v63 offset:17536
	s_waitcnt lgkmcnt(0)
	v_mfma_f32_16x16x32_bf16 v[18:21], v[10:13], v[42:45], v[18:21]
	ds_read_b128 v[10:13], v63 offset:21888
	s_waitcnt lgkmcnt(0)
	v_mfma_f32_16x16x32_bf16 v[22:25], v[10:13], v[42:45], v[22:25]
	ds_read_b128 v[10:13], v63 offset:26240
	s_waitcnt lgkmcnt(0)
	v_mfma_f32_16x16x32_bf16 v[54:57], v[10:13], v[42:45], v[26:29]
	ds_read_b128 v[10:13], v63 offset:30592
	s_waitcnt lgkmcnt(0)
	v_mfma_f32_16x16x32_bf16 v[58:61], v[10:13], v[42:45], v[30:33]
	ds_read_b128 v[34:37], v62 offset:192
	ds_read_b128 v[10:13], v63 offset:192
	ds_read_b128 v[74:77], v72 offset:52224
	ds_read_b128 v[78:81], v72 offset:56576
	ds_read_b128 v[82:85], v72 offset:60928
	s_waitcnt lgkmcnt(3)
	v_mfma_f32_16x16x32_bf16 v[10:13], v[10:13], v[34:37], v[2:5]
	ds_read_b128 v[86:89], v72 offset:65280
	s_nop 1
	ds_read_b128 v[2:5], v63 offset:4544
	s_waitcnt lgkmcnt(0)
	v_mfma_f32_16x16x32_bf16 v[30:33], v[2:5], v[34:37], v[6:9]
	ds_read_b128 v[2:5], v63 offset:8896
	s_nop 1
	ds_read_b128 v[6:9], v63 offset:13248
	s_waitcnt lgkmcnt(0)
; #define LAS __attribute__((address_space(3)))
; __device__ __forceinline__ unsigned pk2(float lo, float hi) { return pg8::cvt_pk_bf16(lo, hi); }
; __device__ __forceinline__ float fexp2(float x) { return __builtin_amdgcn_exp2f(x); }
; __device__ __forceinline__ void ret_unit(LAS unsigned char* lds, const bfu* PROJ, const bfu* RT, const float* gn_g, bfu* CAT, int u) {
;     ...
;     wave_mma(cr, Qs, Rt, m0, fr, fq);
;     wave_mma(acc, Qs, Ks, m0, fr, fq);
;     __syncthreads();
; #pragma unroll
;     for (int t = 0; t < 8; ++t) { float p[4];
; #pragma unroll
;         for (int j = 0; j < 4; ++j) { const int e = 16 * t + 4 * fq + j; p[j] = (c >= e) ? acc[t][j] * fexp2(lg * (float)(c - e)) : 0.f; }
;         v2u w; w.x = pk2(p[0], p[1]); w.y = pk2(p[2], p[3]); *(LAS v2u*)(Ks + c * TS + 16 * t + 4 * fq) = w; }
	v_mfma_f32_16x16x32_bf16 v[14:17], v[6:9], v[34:37], v[14:17]
	ds_read_b128 v[6:9], v63 offset:17600
	v_mfma_f32_16x16x32_bf16 v[2:5], v[2:5], v[34:37], v[50:53]
	s_nop 2
	ds_read_b128 v[50:53], v72 offset:34816
	s_waitcnt lgkmcnt(1)
	v_mfma_f32_16x16x32_bf16 v[26:29], v[6:9], v[34:37], v[18:21]
	ds_read_b128 v[6:9], v63 offset:21952
	s_nop 1
	ds_read_b128 v[18:21], v63 offset:26304
	s_waitcnt lgkmcnt(1)
	v_mfma_f32_16x16x32_bf16 v[6:9], v[6:9], v[34:37], v[22:25]
	s_nop 2
	ds_read_b128 v[22:25], v63 offset:30656
	s_waitcnt lgkmcnt(1)
	v_mfma_f32_16x16x32_bf16 v[18:21], v[18:21], v[34:37], v[54:57]
	s_nop 2
	ds_read_b128 v[54:57], v72 offset:39168
	s_waitcnt lgkmcnt(1)
	v_mfma_f32_16x16x32_bf16 v[22:25], v[22:25], v[34:37], v[58:61]
	ds_read_b128 v[62:65], v72 offset:47872
	s_nop 1
	ds_read_b128 v[58:61], v72 offset:43520
	v_mfma_f32_16x16x32_bf16 v[50:53], v[50:53], v[46:49], 0
	s_waitcnt lgkmcnt(2)
	v_mfma_f32_16x16x32_bf16 v[54:57], v[54:57], v[46:49], 0
	s_waitcnt lgkmcnt(0)
	v_mfma_f32_16x16x32_bf16 v[58:61], v[58:61], v[46:49], 0
	v_mfma_f32_16x16x32_bf16 v[62:65], v[62:65], v[46:49], 0
	v_mfma_f32_16x16x32_bf16 v[74:77], v[74:77], v[46:49], 0
	v_mfma_f32_16x16x32_bf16 v[78:81], v[78:81], v[46:49], 0
	v_mfma_f32_16x16x32_bf16 v[82:85], v[82:85], v[46:49], 0
	v_mfma_f32_16x16x32_bf16 v[46:49], v[86:89], v[46:49], 0
	ds_read_b128 v[86:89], v72 offset:34880
	s_waitcnt lgkmcnt(0)
	v_mfma_f32_16x16x32_bf16 v[50:53], v[86:89], v[38:41], v[50:53]
	ds_read_b128 v[86:89], v72 offset:39232
	s_waitcnt lgkmcnt(0)
	v_mfma_f32_16x16x32_bf16 v[54:57], v[86:89], v[38:41], v[54:57]
	ds_read_b128 v[86:89], v72 offset:43584
	s_waitcnt lgkmcnt(0)
	v_mfma_f32_16x16x32_bf16 v[58:61], v[86:89], v[38:41], v[58:61]
	ds_read_b128 v[86:89], v72 offset:47936
	s_waitcnt lgkmcnt(0)
	v_mfma_f32_16x16x32_bf16 v[62:65], v[86:89], v[38:41], v[62:65]
	ds_read_b128 v[86:89], v72 offset:52288
	s_waitcnt lgkmcnt(0)
	v_mfma_f32_16x16x32_bf16 v[74:77], v[86:89], v[38:41], v[74:77]
	ds_read_b128 v[86:89], v72 offset:56640
	s_waitcnt lgkmcnt(0)
	v_mfma_f32_16x16x32_bf16 v[78:81], v[86:89], v[38:41], v[78:81]
	ds_read_b128 v[86:89], v72 offset:60992
	s_waitcnt lgkmcnt(0)
	v_mfma_f32_16x16x32_bf16 v[82:85], v[86:89], v[38:41], v[82:85]
	ds_read_b128 v[86:89], v72 offset:65344
	s_waitcnt lgkmcnt(0)
	v_mfma_f32_16x16x32_bf16 v[38:41], v[86:89], v[38:41], v[46:49]
	s_nop 2
	ds_read_b128 v[46:49], v72 offset:34944
	s_waitcnt lgkmcnt(0)
	v_mfma_f32_16x16x32_bf16 v[46:49], v[46:49], v[42:45], v[50:53]
	s_nop 2
	ds_read_b128 v[50:53], v72 offset:39296
	s_waitcnt lgkmcnt(0)
	v_mfma_f32_16x16x32_bf16 v[50:53], v[50:53], v[42:45], v[54:57]
	s_nop 2
	ds_read_b128 v[54:57], v72 offset:43648
	s_waitcnt lgkmcnt(0)
	v_mfma_f32_16x16x32_bf16 v[54:57], v[54:57], v[42:45], v[58:61]
	s_nop 2
	ds_read_b128 v[58:61], v72 offset:48000
	s_waitcnt lgkmcnt(0)
	v_mfma_f32_16x16x32_bf16 v[86:89], v[58:61], v[42:45], v[62:65]
	ds_read_b128 v[58:61], v72 offset:52352
	s_waitcnt lgkmcnt(0)
	v_mfma_f32_16x16x32_bf16 v[74:77], v[58:61], v[42:45], v[74:77]
	ds_read_b128 v[58:61], v72 offset:56704
	s_waitcnt lgkmcnt(0)
	v_mfma_f32_16x16x32_bf16 v[78:81], v[58:61], v[42:45], v[78:81]
	ds_read_b128 v[58:61], v72 offset:61056
	s_waitcnt lgkmcnt(0)
	v_mfma_f32_16x16x32_bf16 v[82:85], v[58:61], v[42:45], v[82:85]
	ds_read_b128 v[58:61], v72 offset:65408
	s_waitcnt lgkmcnt(0)
	v_mfma_f32_16x16x32_bf16 v[90:93], v[58:61], v[42:45], v[38:41]
	s_nop 2
	ds_read_b128 v[38:41], v72 offset:35008
	s_waitcnt lgkmcnt(0)
	v_mfma_f32_16x16x32_bf16 v[62:65], v[38:41], v[34:37], v[46:49]
	ds_read_b128 v[38:41], v72 offset:39360
	s_waitcnt lgkmcnt(0)
	v_mfma_f32_16x16x32_bf16 v[58:61], v[38:41], v[34:37], v[50:53]
	ds_read_b128 v[38:41], v72 offset:43712
	s_waitcnt lgkmcnt(0)
	v_mfma_f32_16x16x32_bf16 v[54:57], v[38:41], v[34:37], v[54:57]
	ds_read_b128 v[38:41], v72 offset:48064
	s_waitcnt lgkmcnt(0)
	v_mfma_f32_16x16x32_bf16 v[50:53], v[38:41], v[34:37], v[86:89]
	ds_read_b128 v[38:41], v72 offset:52416
	s_waitcnt lgkmcnt(0)
	v_mfma_f32_16x16x32_bf16 v[46:49], v[38:41], v[34:37], v[74:77]
	ds_read_b128 v[38:41], v72 offset:56768
	s_nop 1
	ds_read_b128 v[74:77], v72 offset:65472
	s_waitcnt lgkmcnt(1)
	v_mfma_f32_16x16x32_bf16 v[42:45], v[38:41], v[34:37], v[78:81]
	ds_read_b128 v[38:41], v72 offset:61120
	v_lshlrev_b32_e32 v72, 2, v71
	v_add_u32_e32 v71, v73, v0
	v_sub_u32_e32 v73, v66, v72
	v_cvt_f32_i32_e32 v73, v73
	v_cmp_ge_i32_e32 vcc, v66, v72
	s_waitcnt lgkmcnt(0)
	v_mfma_f32_16x16x32_bf16 v[38:41], v[38:41], v[34:37], v[82:85]
	v_mul_f32_e32 v73, v67, v73
	v_exp_f32_e32 v73, v73
	v_mfma_f32_16x16x32_bf16 v[34:37], v[74:77], v[34:37], v[90:93]
	v_or_b32_e32 v75, 3, v72
	v_mul_f32_e32 v62, v73, v62
	v_cndmask_b32_e32 v73, 0, v62, vcc
	v_xad_u32 v62, v72, -1, v66
	v_cvt_f32_i32_e32 v62, v62
	v_cmp_gt_i32_e32 vcc, v66, v72
	v_or_b32_e32 v76, 2, v72
	s_barrier
; #define LAS __attribute__((address_space(3)))
; #define LDS_WAIT() asm volatile("s_waitcnt lgkmcnt(0)" ::: "memory")
; __device__ __forceinline__ unsigned pk2(float lo, float hi) { return pg8::cvt_pk_bf16(lo, hi); }
; __device__ __forceinline__ float fexp2(float x) { return __builtin_amdgcn_exp2f(x); }
; __device__ __forceinline__ void ret_unit(LAS unsigned char* lds, const bfu* PROJ, const bfu* RT, const float* gn_g, bfu* CAT, int u) {
;     ...
;     for (int t = 0; t < 8; ++t) { float p[4];
; #pragma unroll
;         for (int j = 0; j < 4; ++j) { const int e = 16 * t + 4 * fq + j; p[j] = (c >= e) ? acc[t][j] * fexp2(lg * (float)(c - e)) : 0.f; }
;         v2u w; w.x = pk2(p[0], p[1]); w.y = pk2(p[2], p[3]); *(LAS v2u*)(Ks + c * TS + 16 * t + 4 * fq) = w; }
;     LDS_WAIT(); asm volatile("" ::: "memory");
	v_mul_f32_e32 v62, v67, v62
	v_exp_f32_e32 v62, v62
	v_add_u32_e32 v78, v71, v0
	v_add3_u32 v82, s70, v69, v70
	v_mul_f32_e32 v62, v62, v63
	v_cndmask_b32_e32 v74, 0, v62, vcc
	v_sub_u32_e32 v62, v66, v76
	v_sub_u32_e32 v63, v66, v75
	v_cvt_f32_i32_e32 v62, v62
	v_cvt_f32_i32_e32 v63, v63
	v_cmp_ge_i32_e32 vcc, v66, v76
	v_or_b32_e32 v76, 18, v72
	v_mul_f32_e32 v62, v67, v62
	v_mul_f32_e32 v63, v67, v63
	v_exp_f32_e32 v62, v62
	v_exp_f32_e32 v63, v63
	s_nop 0
	v_pk_mul_f32 v[62:63], v[62:63], v[64:65]
	s_nop 0
	v_cvt_pk_bf16_f32 v62, v62, v63
	v_cndmask_b32_e32 v63, 0, v62, vcc
	v_lshrrev_b32_e32 v62, 16, v62
	v_cmp_ge_i32_e32 vcc, v66, v75
	v_cvt_pk_bf16_f32 v64, v73, v74
	v_or_b32_e32 v73, 17, v72
	v_cndmask_b32_e32 v62, 0, v62, vcc
	v_or_b32_e32 v74, 16, v72
	v_perm_b32 v65, v62, v63, s72
	v_sub_u32_e32 v62, v66, v74
	v_sub_u32_e32 v63, v66, v73
	v_cvt_f32_i32_e32 v62, v62
	v_cvt_f32_i32_e32 v63, v63
	v_or_b32_e32 v75, 19, v72
	v_cmp_ge_i32_e32 vcc, v66, v74
	v_mul_f32_e32 v62, v67, v62
	v_mul_f32_e32 v63, v67, v63
	v_exp_f32_e32 v62, v62
	v_exp_f32_e32 v63, v63
	s_nop 0
	v_pk_mul_f32 v[58:59], v[62:63], v[58:59]
	v_sub_u32_e32 v62, v66, v76
	v_sub_u32_e32 v63, v66, v75
	v_cvt_f32_i32_e32 v62, v62
	v_cvt_f32_i32_e32 v63, v63
	v_cvt_pk_bf16_f32 v58, v58, v59
	v_cndmask_b32_e32 v59, 0, v58, vcc
	v_mul_f32_e32 v62, v67, v62
	v_mul_f32_e32 v63, v67, v63
	v_exp_f32_e32 v62, v62
	v_exp_f32_e32 v63, v63
	v_lshrrev_b32_e32 v58, 16, v58
	v_cmp_ge_i32_e32 vcc, v66, v73
	v_pk_mul_f32 v[60:61], v[62:63], v[60:61]
	s_nop 0
	v_cndmask_b32_e32 v58, 0, v58, vcc
	v_perm_b32 v62, v58, v59, s72
	v_cvt_pk_bf16_f32 v58, v60, v61
	v_cmp_ge_i32_e32 vcc, v66, v76
	s_nop 1
	v_cndmask_b32_e32 v59, 0, v58, vcc
	v_lshrrev_b32_e32 v58, 16, v58
	v_cmp_ge_i32_e32 vcc, v66, v75
	s_nop 1
	v_cndmask_b32_e32 v58, 0, v58, vcc
	v_perm_b32 v63, v58, v59, s72
	v_add_u32_e32 v58, 0x8800, v71
	ds_write2_b64 v58, v[64:65], v[62:63] offset1:4
	v_or_b32_e32 v59, 33, v72
	v_or_b32_e32 v62, 32, v72
	v_sub_u32_e32 v60, v66, v62
	v_sub_u32_e32 v61, v66, v59
	v_cvt_f32_i32_e32 v60, v60
	v_cvt_f32_i32_e32 v61, v61
	v_or_b32_e32 v63, 35, v72
	v_or_b32_e32 v64, 34, v72
	v_mul_f32_e32 v60, v67, v60
	v_mul_f32_e32 v61, v67, v61
	v_exp_f32_e32 v60, v60
	v_exp_f32_e32 v61, v61
	v_cmp_ge_i32_e32 vcc, v66, v62
	v_or_b32_e32 v62, 50, v72
	v_pk_mul_f32 v[54:55], v[60:61], v[54:55]
	v_sub_u32_e32 v60, v66, v64
	v_sub_u32_e32 v61, v66, v63
	v_cvt_f32_i32_e32 v60, v60
	v_cvt_f32_i32_e32 v61, v61
	v_cvt_pk_bf16_f32 v54, v54, v55
	v_cndmask_b32_e32 v55, 0, v54, vcc
	v_mul_f32_e32 v60, v67, v60
	v_mul_f32_e32 v61, v67, v61
	v_exp_f32_e32 v60, v60
	v_exp_f32_e32 v61, v61
	v_lshrrev_b32_e32 v54, 16, v54
	v_cmp_ge_i32_e32 vcc, v66, v59
	v_or_b32_e32 v59, 49, v72
	v_pk_mul_f32 v[56:57], v[60:61], v[56:57]
	v_cndmask_b32_e32 v54, 0, v54, vcc
	v_perm_b32 v54, v54, v55, s72
	v_cvt_pk_bf16_f32 v55, v56, v57
	v_cmp_ge_i32_e32 vcc, v66, v64
	v_or_b32_e32 v60, 48, v72
	v_sub_u32_e32 v57, v66, v59
	v_cndmask_b32_e32 v56, 0, v55, vcc
	v_lshrrev_b32_e32 v55, 16, v55
	v_cmp_ge_i32_e32 vcc, v66, v63
	v_cvt_f32_i32_e32 v57, v57
	v_or_b32_e32 v61, 51, v72
	v_cndmask_b32_e32 v55, 0, v55, vcc
	v_perm_b32 v55, v55, v56, s72
	v_sub_u32_e32 v56, v66, v60
	v_cvt_f32_i32_e32 v56, v56
	v_mul_f32_e32 v57, v67, v57
	v_exp_f32_e32 v57, v57
	v_cmp_ge_i32_e32 vcc, v66, v60
	v_mul_f32_e32 v56, v67, v56
	v_exp_f32_e32 v56, v56
	s_nop 0
	v_pk_mul_f32 v[50:51], v[56:57], v[50:51]
	v_sub_u32_e32 v56, v66, v62
	v_sub_u32_e32 v57, v66, v61
	v_cvt_f32_i32_e32 v56, v56
	v_cvt_f32_i32_e32 v57, v57
	v_cvt_pk_bf16_f32 v50, v50, v51
	v_cndmask_b32_e32 v51, 0, v50, vcc
	v_mul_f32_e32 v56, v67, v56
	v_mul_f32_e32 v57, v67, v57
	v_exp_f32_e32 v56, v56
	v_exp_f32_e32 v57, v57
	v_lshrrev_b32_e32 v50, 16, v50
	v_cmp_ge_i32_e32 vcc, v66, v59
	v_pk_mul_f32 v[52:53], v[56:57], v[52:53]
	s_nop 0
	v_cndmask_b32_e32 v50, 0, v50, vcc
	v_perm_b32 v50, v50, v51, s72
	v_cvt_pk_bf16_f32 v51, v52, v53
	v_cmp_ge_i32_e32 vcc, v66, v62
	v_or_b32_e32 v53, 64, v72
	s_nop 0
	v_cndmask_b32_e32 v52, 0, v51, vcc
	v_lshrrev_b32_e32 v51, 16, v51
	v_cmp_ge_i32_e32 vcc, v66, v61
	s_nop 1
	v_cndmask_b32_e32 v51, 0, v51, vcc
	v_perm_b32 v51, v51, v52, s72
	v_or_b32_e32 v52, 0x41, v72
	ds_write2_b64 v58, v[54:55], v[50:51] offset0:8 offset1:12
	v_sub_u32_e32 v50, v66, v53
	v_sub_u32_e32 v51, v66, v52
	v_cvt_f32_i32_e32 v50, v50
	v_cvt_f32_i32_e32 v51, v51
	v_or_b32_e32 v54, 0x43, v72
	v_or_b32_e32 v55, 0x42, v72
	v_mul_f32_e32 v50, v67, v50
	v_mul_f32_e32 v51, v67, v51
	v_exp_f32_e32 v50, v50
	v_exp_f32_e32 v51, v51
	v_cmp_ge_i32_e32 vcc, v66, v53
	v_or_b32_e32 v53, 0x52, v72
	v_pk_mul_f32 v[46:47], v[50:51], v[46:47]
	v_sub_u32_e32 v50, v66, v55
	v_sub_u32_e32 v51, v66, v54
	v_cvt_f32_i32_e32 v50, v50
	v_cvt_f32_i32_e32 v51, v51
	v_cvt_pk_bf16_f32 v46, v46, v47
	v_cndmask_b32_e32 v47, 0, v46, vcc
	v_mul_f32_e32 v50, v67, v50
	v_mul_f32_e32 v51, v67, v51
	v_exp_f32_e32 v50, v50
	v_exp_f32_e32 v51, v51
	v_lshrrev_b32_e32 v46, 16, v46
	v_cmp_ge_i32_e32 vcc, v66, v52
	v_or_b32_e32 v52, 0x53, v72
	v_pk_mul_f32 v[48:49], v[50:51], v[48:49]
	v_cndmask_b32_e32 v46, 0, v46, vcc
	v_perm_b32 v46, v46, v47, s72
	v_cvt_pk_bf16_f32 v47, v48, v49
	v_cmp_ge_i32_e32 vcc, v66, v55
	v_or_b32_e32 v50, 0x51, v72
	v_or_b32_e32 v51, 0x50, v72
	v_cndmask_b32_e32 v48, 0, v47, vcc
	v_lshrrev_b32_e32 v47, 16, v47
	v_cmp_ge_i32_e32 vcc, v66, v54
	v_sub_u32_e32 v49, v66, v50
	v_cvt_f32_i32_e32 v49, v49
	v_cndmask_b32_e32 v47, 0, v47, vcc
	v_perm_b32 v47, v47, v48, s72
	v_sub_u32_e32 v48, v66, v51
	v_cvt_f32_i32_e32 v48, v48
	v_mul_f32_e32 v49, v67, v49
	v_exp_f32_e32 v49, v49
	v_cmp_ge_i32_e32 vcc, v66, v51
; #define LAS __attribute__((address_space(3)))
; #define LDS_WAIT() asm volatile("s_waitcnt lgkmcnt(0)" ::: "memory")
; __device__ __forceinline__ unsigned pk2(float lo, float hi) { return pg8::cvt_pk_bf16(lo, hi); }
; __device__ __forceinline__ float fexp2(float x) { return __builtin_amdgcn_exp2f(x); }
; #define ZERO8(a) do { _Pragma("unroll") for (int t_ = 0; t_ < 8; ++t_) a[t_] = (f32x4){0.f, 0.f, 0.f, 0.f}; } while (0)
; __device__ __forceinline__ void ret_unit(LAS unsigned char* lds, const bfu* PROJ, const bfu* RT, const float* gn_g, bfu* CAT, int u) {
;     ...
;     for (int t = 0; t < 8; ++t) { float p[4];
; #pragma unroll
;         for (int j = 0; j < 4; ++j) { const int e = 16 * t + 4 * fq + j; p[j] = (c >= e) ? acc[t][j] * fexp2(lg * (float)(c - e)) : 0.f; }
;         v2u w; w.x = pk2(p[0], p[1]); w.y = pk2(p[2], p[3]); *(LAS v2u*)(Ks + c * TS + 16 * t + 4 * fq) = w; }
;     LDS_WAIT(); asm volatile("" ::: "memory");
;     ZERO8(acc);
;     wave_mma(acc, Ks, Vt, m0, fr, fq);
	v_mul_f32_e32 v48, v67, v48
	v_exp_f32_e32 v48, v48
	s_nop 0
	v_pk_mul_f32 v[42:43], v[48:49], v[42:43]
	v_sub_u32_e32 v48, v66, v53
	v_sub_u32_e32 v49, v66, v52
	v_cvt_f32_i32_e32 v48, v48
	v_cvt_f32_i32_e32 v49, v49
	v_cvt_pk_bf16_f32 v42, v42, v43
	v_cndmask_b32_e32 v43, 0, v42, vcc
	v_mul_f32_e32 v48, v67, v48
	v_mul_f32_e32 v49, v67, v49
	v_exp_f32_e32 v48, v48
	v_exp_f32_e32 v49, v49
	v_lshrrev_b32_e32 v42, 16, v42
	v_cmp_ge_i32_e32 vcc, v66, v50
	v_pk_mul_f32 v[44:45], v[48:49], v[44:45]
	s_nop 0
	v_cndmask_b32_e32 v42, 0, v42, vcc
	v_perm_b32 v42, v42, v43, s72
	v_cvt_pk_bf16_f32 v43, v44, v45
	v_cmp_ge_i32_e32 vcc, v66, v53
	v_or_b32_e32 v45, 0x60, v72
	s_nop 0
	v_cndmask_b32_e32 v44, 0, v43, vcc
	v_lshrrev_b32_e32 v43, 16, v43
	v_cmp_ge_i32_e32 vcc, v66, v52
	s_nop 1
	v_cndmask_b32_e32 v43, 0, v43, vcc
	v_perm_b32 v43, v43, v44, s72
	v_or_b32_e32 v44, 0x61, v72
	ds_write2_b64 v58, v[46:47], v[42:43] offset0:16 offset1:20
	v_sub_u32_e32 v42, v66, v45
	v_sub_u32_e32 v43, v66, v44
	v_cvt_f32_i32_e32 v42, v42
	v_cvt_f32_i32_e32 v43, v43
	v_or_b32_e32 v46, 0x63, v72
	v_or_b32_e32 v47, 0x62, v72
	v_mul_f32_e32 v42, v67, v42
	v_mul_f32_e32 v43, v67, v43
	v_exp_f32_e32 v42, v42
	v_exp_f32_e32 v43, v43
	v_cmp_ge_i32_e32 vcc, v66, v45
	v_or_b32_e32 v45, 0x72, v72
	v_pk_mul_f32 v[38:39], v[42:43], v[38:39]
	v_sub_u32_e32 v42, v66, v47
	v_sub_u32_e32 v43, v66, v46
	v_cvt_f32_i32_e32 v42, v42
	v_cvt_f32_i32_e32 v43, v43
	v_cvt_pk_bf16_f32 v38, v38, v39
	v_cndmask_b32_e32 v39, 0, v38, vcc
	v_mul_f32_e32 v42, v67, v42
	v_mul_f32_e32 v43, v67, v43
	v_exp_f32_e32 v42, v42
	v_exp_f32_e32 v43, v43
	v_lshrrev_b32_e32 v38, 16, v38
	v_cmp_ge_i32_e32 vcc, v66, v44
	v_or_b32_e32 v44, 0x73, v72
	v_pk_mul_f32 v[40:41], v[42:43], v[40:41]
	v_cndmask_b32_e32 v38, 0, v38, vcc
	v_perm_b32 v38, v38, v39, s72
	v_cvt_pk_bf16_f32 v39, v40, v41
	v_cmp_ge_i32_e32 vcc, v66, v47
	v_or_b32_e32 v42, 0x71, v72
	v_or_b32_e32 v43, 0x70, v72
	v_cndmask_b32_e32 v40, 0, v39, vcc
	v_lshrrev_b32_e32 v39, 16, v39
	v_cmp_ge_i32_e32 vcc, v66, v46
	v_sub_u32_e32 v41, v66, v42
	v_cvt_f32_i32_e32 v41, v41
	v_cndmask_b32_e32 v39, 0, v39, vcc
	v_perm_b32 v39, v39, v40, s72
	v_sub_u32_e32 v40, v66, v43
	v_cvt_f32_i32_e32 v40, v40
	v_mul_f32_e32 v41, v67, v41
	v_exp_f32_e32 v41, v41
	v_cmp_ge_i32_e32 vcc, v66, v43
	v_mul_f32_e32 v40, v67, v40
	v_exp_f32_e32 v40, v40
	s_nop 0
	v_pk_mul_f32 v[34:35], v[40:41], v[34:35]
	v_sub_u32_e32 v40, v66, v45
	v_sub_u32_e32 v41, v66, v44
	v_cvt_f32_i32_e32 v40, v40
	v_cvt_f32_i32_e32 v41, v41
	v_cvt_pk_bf16_f32 v34, v34, v35
	v_cndmask_b32_e32 v35, 0, v34, vcc
	v_mul_f32_e32 v40, v67, v40
	v_mul_f32_e32 v41, v67, v41
	v_exp_f32_e32 v40, v40
	v_exp_f32_e32 v41, v41
	v_lshrrev_b32_e32 v34, 16, v34
	v_cmp_ge_i32_e32 vcc, v66, v42
	v_pk_mul_f32 v[36:37], v[40:41], v[36:37]
	s_nop 0
	v_cndmask_b32_e32 v34, 0, v34, vcc
	v_perm_b32 v34, v34, v35, s72
	v_cvt_pk_bf16_f32 v35, v36, v37
	v_cmp_ge_i32_e32 vcc, v66, v45
	s_nop 1
	v_cndmask_b32_e32 v36, 0, v35, vcc
	v_lshrrev_b32_e32 v35, 16, v35
	v_cmp_ge_i32_e32 vcc, v66, v44
	s_nop 1
	v_cndmask_b32_e32 v35, 0, v35, vcc
	v_perm_b32 v35, v35, v36, s72
	ds_write2_b64 v58, v[38:39], v[34:35] offset0:24 offset1:28
	s_waitcnt lgkmcnt(0)
	ds_read_b128 v[34:37], v78 offset:34816
	ds_read_b128 v[38:41], v82
	ds_read_b128 v[42:45], v82 offset:4352
	ds_read_b128 v[46:49], v82 offset:8704
	ds_read_b128 v[50:53], v82 offset:13056
	ds_read_b128 v[54:57], v82 offset:17408
	ds_read_b128 v[58:61], v82 offset:21760
	ds_read_b128 v[62:65], v82 offset:26112
	ds_read_b128 v[70:73], v82 offset:30464
	s_waitcnt lgkmcnt(7)
	v_mfma_f32_16x16x32_bf16 v[38:41], v[38:41], v[34:37], 0
	s_waitcnt lgkmcnt(6)
	v_mfma_f32_16x16x32_bf16 v[42:45], v[42:45], v[34:37], 0
	s_waitcnt lgkmcnt(5)
	v_mfma_f32_16x16x32_bf16 v[46:49], v[46:49], v[34:37], 0
	s_waitcnt lgkmcnt(4)
	v_mfma_f32_16x16x32_bf16 v[50:53], v[50:53], v[34:37], 0
	s_waitcnt lgkmcnt(3)
	v_mfma_f32_16x16x32_bf16 v[54:57], v[54:57], v[34:37], 0
	s_waitcnt lgkmcnt(2)
	v_mfma_f32_16x16x32_bf16 v[58:61], v[58:61], v[34:37], 0
	s_waitcnt lgkmcnt(1)
	v_mfma_f32_16x16x32_bf16 v[62:65], v[62:65], v[34:37], 0
	s_waitcnt lgkmcnt(0)
	v_mfma_f32_16x16x32_bf16 v[34:37], v[70:73], v[34:37], 0
	ds_read_b128 v[70:73], v78 offset:34880
	ds_read_b128 v[74:77], v82 offset:64
	s_waitcnt lgkmcnt(0)
	v_mfma_f32_16x16x32_bf16 v[38:41], v[74:77], v[70:73], v[38:41]
	ds_read_b128 v[74:77], v82 offset:4416
	s_waitcnt lgkmcnt(0)
	v_mfma_f32_16x16x32_bf16 v[42:45], v[74:77], v[70:73], v[42:45]
	ds_read_b128 v[74:77], v82 offset:8768
	s_waitcnt lgkmcnt(0)
	v_mfma_f32_16x16x32_bf16 v[46:49], v[74:77], v[70:73], v[46:49]
	ds_read_b128 v[74:77], v82 offset:13120
	s_waitcnt lgkmcnt(0)
	v_mfma_f32_16x16x32_bf16 v[50:53], v[74:77], v[70:73], v[50:53]
	ds_read_b128 v[74:77], v82 offset:17472
	s_waitcnt lgkmcnt(0)
	v_mfma_f32_16x16x32_bf16 v[54:57], v[74:77], v[70:73], v[54:57]
	ds_read_b128 v[74:77], v82 offset:21824
	s_waitcnt lgkmcnt(0)
	v_mfma_f32_16x16x32_bf16 v[58:61], v[74:77], v[70:73], v[58:61]
	ds_read_b128 v[74:77], v82 offset:26176
	s_waitcnt lgkmcnt(0)
	v_mfma_f32_16x16x32_bf16 v[62:65], v[74:77], v[70:73], v[62:65]
	ds_read_b128 v[74:77], v82 offset:30528
	s_waitcnt lgkmcnt(0)
	v_mfma_f32_16x16x32_bf16 v[34:37], v[74:77], v[70:73], v[34:37]
	ds_read_b128 v[70:73], v78 offset:34944
	ds_read_b128 v[74:77], v82 offset:128
	s_waitcnt lgkmcnt(0)
	v_mfma_f32_16x16x32_bf16 v[38:41], v[74:77], v[70:73], v[38:41]
	ds_read_b128 v[74:77], v82 offset:4480
	s_waitcnt lgkmcnt(0)
	v_mfma_f32_16x16x32_bf16 v[42:45], v[74:77], v[70:73], v[42:45]
	ds_read_b128 v[74:77], v82 offset:8832
	s_waitcnt lgkmcnt(0)
; __device__ __forceinline__ float fexp2(float x) { return __builtin_amdgcn_exp2f(x); }
; __device__ __forceinline__ void ret_unit(LAS unsigned char* lds, const bfu* PROJ, const bfu* RT, const float* gn_g, bfu* CAT, int u) {
;     ...
;     wave_mma(acc, Ks, Vt, m0, fr, fq);
;     const float xi = fexp2(lg * (float)(c + 1)); float s = 0.f;
; #pragma unroll
;     for (int t = 0; t < 8; ++t) { acc[t] = acc[t] + cr[t] * xi; s += (acc[t][0] + acc[t][1]) + (acc[t][2] + acc[t][3]); }
;     s += __shfl_xor(s, 16); s += __shfl_xor(s, 32); const float mu = s * (1.f / 128.f); float q = 0.f;
	v_mfma_f32_16x16x32_bf16 v[46:49], v[74:77], v[70:73], v[46:49]
	ds_read_b128 v[74:77], v82 offset:13184
	s_waitcnt lgkmcnt(0)
	v_mfma_f32_16x16x32_bf16 v[50:53], v[74:77], v[70:73], v[50:53]
	ds_read_b128 v[74:77], v82 offset:17536
	s_waitcnt lgkmcnt(0)
	v_mfma_f32_16x16x32_bf16 v[54:57], v[74:77], v[70:73], v[54:57]
	ds_read_b128 v[74:77], v82 offset:21888
	s_waitcnt lgkmcnt(0)
	v_mfma_f32_16x16x32_bf16 v[58:61], v[74:77], v[70:73], v[58:61]
	ds_read_b128 v[74:77], v82 offset:26240
	s_waitcnt lgkmcnt(0)
	v_mfma_f32_16x16x32_bf16 v[62:65], v[74:77], v[70:73], v[62:65]
	ds_read_b128 v[74:77], v82 offset:30592
	s_waitcnt lgkmcnt(0)
	v_mfma_f32_16x16x32_bf16 v[34:37], v[74:77], v[70:73], v[34:37]
	ds_read_b128 v[70:73], v78 offset:35008
	ds_read_b128 v[74:77], v82 offset:192
	s_waitcnt lgkmcnt(0)
	v_mfma_f32_16x16x32_bf16 v[38:41], v[74:77], v[70:73], v[38:41]
	ds_read_b128 v[74:77], v82 offset:4544
	s_waitcnt lgkmcnt(0)
	v_mfma_f32_16x16x32_bf16 v[74:77], v[74:77], v[70:73], v[42:45]
	s_nop 2
	ds_read_b128 v[42:45], v82 offset:8896
	s_waitcnt lgkmcnt(0)
	v_mfma_f32_16x16x32_bf16 v[78:81], v[42:45], v[70:73], v[46:49]
	ds_read_b128 v[42:45], v82 offset:13248
	s_waitcnt lgkmcnt(0)
	v_mfma_f32_16x16x32_bf16 v[48:51], v[42:45], v[70:73], v[50:53]
	ds_read_b128 v[42:45], v82 offset:17600
	s_waitcnt lgkmcnt(0)
	v_mfma_f32_16x16x32_bf16 v[52:55], v[42:45], v[70:73], v[54:57]
	ds_read_b128 v[42:45], v82 offset:21952
	s_waitcnt lgkmcnt(0)
	v_mfma_f32_16x16x32_bf16 v[56:59], v[42:45], v[70:73], v[58:61]
	ds_read_b128 v[42:45], v82 offset:26304
	s_waitcnt lgkmcnt(0)
	v_mfma_f32_16x16x32_bf16 v[60:63], v[42:45], v[70:73], v[62:65]
	ds_read_b128 v[42:45], v82 offset:30656
	s_waitcnt lgkmcnt(0)
	v_mfma_f32_16x16x32_bf16 v[70:73], v[42:45], v[70:73], v[34:37]
	s_nop 2
	v_add_u32_e32 v34, 1, v66
	v_cvt_f32_i32_e32 v34, v34
	v_mul_f32_e32 v34, v67, v34
	v_exp_f32_e32 v64, v34
	v_ashrrev_i32_e32 v67, 31, v66
	v_pk_fma_f32 v[46:47], v[64:65], v[10:11], v[38:39] op_sel_hi:[0,1,1]
	v_pk_fma_f32 v[42:43], v[64:65], v[30:31], v[74:75] op_sel_hi:[0,1,1]
	v_pk_fma_f32 v[44:45], v[64:65], v[12:13], v[40:41] op_sel_hi:[0,1,1]
	v_pk_fma_f32 v[40:41], v[64:65], v[32:33], v[76:77] op_sel_hi:[0,1,1]
	v_mov_b32_e32 v10, v46
	v_mov_b32_e32 v11, v42
	v_mov_b32_e32 v12, v47
	v_mov_b32_e32 v13, v43
	v_pk_add_f32 v[10:11], v[10:11], v[12:13]
	v_mov_b32_e32 v12, v44
	v_mov_b32_e32 v13, v40
	v_mov_b32_e32 v30, v45
	v_mov_b32_e32 v31, v41
	v_pk_fma_f32 v[38:39], v[64:65], v[2:3], v[78:79] op_sel_hi:[0,1,1]
	v_pk_fma_f32 v[36:37], v[64:65], v[4:5], v[80:81] op_sel_hi:[0,1,1]
	v_pk_add_f32 v[12:13], v[12:13], v[30:31]
	v_pk_mov_b32 v[2:3], v[38:39], v[36:37] op_sel:[1,0]
	v_mov_b32_e32 v4, v38
	v_mov_b32_e32 v5, v37
	v_pk_add_f32 v[10:11], v[10:11], v[12:13]
	v_pk_add_f32 v[2:3], v[2:3], v[4:5]
	v_add_f32_e32 v10, 0, v10
	v_pk_add_f32 v[2:3], v[2:3], v[2:3] op_sel:[0,1] op_sel_hi:[1,0]
	v_pk_fma_f32 v[32:33], v[64:65], v[16:17], v[50:51] op_sel_hi:[0,1,1]
	v_pk_fma_f32 v[34:35], v[64:65], v[14:15], v[48:49] op_sel_hi:[0,1,1]
	v_pk_fma_f32 v[28:29], v[64:65], v[28:29], v[54:55] op_sel_hi:[0,1,1]
	v_pk_fma_f32 v[30:31], v[64:65], v[26:27], v[52:53] op_sel_hi:[0,1,1]
	v_add_f32_e32 v10, v10, v11
	v_add_f32_e32 v4, v34, v35
	v_add_f32_e32 v12, v32, v33
	v_mov_b32_e32 v11, v30
	v_mov_b32_e32 v3, v31
	v_mov_b32_e32 v5, v28
	v_mov_b32_e32 v13, v29
	v_pk_add_f32 v[2:3], v[10:11], v[2:3]
	v_pk_add_f32 v[4:5], v[4:5], v[12:13]
	v_pk_fma_f32 v[26:27], v[64:65], v[6:7], v[56:57] op_sel_hi:[0,1,1]
	v_pk_fma_f32 v[16:17], v[64:65], v[8:9], v[58:59] op_sel_hi:[0,1,1]
	v_pk_add_f32 v[2:3], v[2:3], v[4:5]
	v_pk_mov_b32 v[4:5], v[26:27], v[16:17] op_sel:[1,0]
	v_mov_b32_e32 v6, v26
	v_mov_b32_e32 v7, v17
	v_pk_add_f32 v[4:5], v[4:5], v[6:7]
	v_pk_add_f32 v[2:3], v[2:3], v[2:3] op_sel:[0,1] op_sel_hi:[1,0]
	v_pk_add_f32 v[4:5], v[4:5], v[4:5] op_sel:[0,1] op_sel_hi:[1,0]
	v_pk_fma_f32 v[10:11], v[64:65], v[20:21], v[62:63] op_sel_hi:[0,1,1]
	v_pk_fma_f32 v[12:13], v[64:65], v[18:19], v[60:61] op_sel_hi:[0,1,1]
	v_pk_fma_f32 v[6:7], v[64:65], v[24:25], v[72:73] op_sel_hi:[0,1,1]
	v_pk_fma_f32 v[8:9], v[64:65], v[22:23], v[70:71] op_sel_hi:[0,1,1]
	v_add_f32_e32 v14, v12, v13
	v_add_f32_e32 v18, v10, v11
	v_mov_b32_e32 v3, v8
	v_mov_b32_e32 v5, v9
	v_mov_b32_e32 v15, v6
	v_mov_b32_e32 v19, v7
	v_pk_add_f32 v[2:3], v[2:3], v[4:5]
	v_pk_add_f32 v[4:5], v[14:15], v[18:19]
	s_nop 0
	v_pk_add_f32 v[2:3], v[2:3], v[4:5]
	v_and_b32_e32 v4, 64, v240
	v_add_f32_e32 v2, v2, v3
	v_xor_b32_e32 v3, 16, v240
	v_add_u32_e32 v4, 64, v4
	v_cmp_lt_i32_e32 vcc, v3, v4
	s_nop 1
	v_cndmask_b32_e32 v3, v240, v3, vcc
	v_lshlrev_b32_e32 v20, 2, v3
	ds_bpermute_b32 v3, v20, v2
	s_waitcnt lgkmcnt(0)
	v_add_f32_e32 v2, v2, v3
	v_xor_b32_e32 v3, 32, v240
	v_cmp_lt_i32_e32 vcc, v3, v4
	s_nop 1
	v_cndmask_b32_e32 v3, v240, v3, vcc
	v_lshlrev_b32_e32 v21, 2, v3
	ds_bpermute_b32 v3, v21, v2
	s_waitcnt lgkmcnt(0)
; __device__ __forceinline__ void ret_unit(LAS unsigned char* lds, const bfu* PROJ, const bfu* RT, const float* gn_g, bfu* CAT, int u) {
;     ...
;     s += __shfl_xor(s, 16); s += __shfl_xor(s, 32); const float mu = s * (1.f / 128.f); float q = 0.f;
; #pragma unroll
;     for (int t = 0; t < 8; ++t) { acc[t] = acc[t] - mu; q += (acc[t][0] * acc[t][0] + acc[t][1] * acc[t][1]) + (acc[t][2] * acc[t][2] + acc[t][3] * acc[t][3]); }
;     q += __shfl_xor(q, 16); q += __shfl_xor(q, 32); const float rstd = 1.f / sqrtf(q * (1.f / 128.f) + EPS);
;     const bfu* gp = P0 + (size_t)c * INW + C_RG + 4 * fq; bfu* op = CAT + (row0 + c) * DM + h * 128 + 4 * fq; const float* gg = gn_g + h * 128 + 4 * fq;
; #pragma unroll
;     for (int t = 0; t < 8; ++t) { const v2u gw = *(const v2u*)(gp + 16 * t); const f32x4 g4 = *(const f32x4*)(gg + 16 * t);
	v_add_f32_e32 v22, v2, v3
	v_fmamk_f32 v47, v22, 0xbc000000, v47
	v_fmamk_f32 v43, v22, 0xbc000000, v43
	v_fmamk_f32 v45, v22, 0xbc000000, v45
	v_fmac_f32_e32 v46, 0xbc000000, v22
	v_fmamk_f32 v41, v22, 0xbc000000, v41
	v_fmac_f32_e32 v42, 0xbc000000, v22
	v_mov_b32_e32 v4, v47
	v_mov_b32_e32 v5, v43
	v_fmac_f32_e32 v44, 0xbc000000, v22
	v_fmac_f32_e32 v40, 0xbc000000, v22
	v_mov_b32_e32 v2, v46
	v_mov_b32_e32 v3, v42
	v_pk_mul_f32 v[4:5], v[4:5], v[4:5]
	v_mov_b32_e32 v14, v45
	v_mov_b32_e32 v15, v41
	v_pk_fma_f32 v[2:3], v[2:3], v[2:3], v[4:5]
	v_mov_b32_e32 v4, v44
	v_mov_b32_e32 v5, v40
	v_pk_mul_f32 v[14:15], v[14:15], v[14:15]
	v_fmamk_f32 v39, v22, 0xbc000000, v39
	v_pk_fma_f32 v[4:5], v[4:5], v[4:5], v[14:15]
	v_fmac_f32_e32 v38, 0xbc000000, v22
	v_pk_add_f32 v[2:3], v[2:3], v[4:5]
	v_fmamk_f32 v37, v22, 0xbc000000, v37
	v_fmac_f32_e32 v36, 0xbc000000, v22
	v_pk_add_f32 v[2:3], v[2:3], v[2:3] op_sel_hi:[0,1]
	v_pk_mul_f32 v[4:5], v[36:37], v[36:37]
	v_pk_mul_f32 v[14:15], v[38:39], v[38:39]
	v_fmac_f32_e32 v34, 0xbc000000, v22
	v_pk_mov_b32 v[18:19], v[14:15], v[4:5] op_sel:[1,0]
	v_mov_b32_e32 v15, v5
	v_fmac_f32_e32 v32, 0xbc000000, v22
	v_fmamk_f32 v35, v22, 0xbc000000, v35
	v_mul_f32_e32 v2, v34, v34
	v_pk_add_f32 v[4:5], v[18:19], v[14:15]
	v_fmamk_f32 v33, v22, 0xbc000000, v33
	v_pk_fma_f32 v[14:15], v[34:35], v[34:35], v[2:3] op_sel_hi:[1,1,0]
	v_mul_f32_e32 v2, v32, v32
	v_pk_add_f32 v[4:5], v[4:5], v[4:5] op_sel_hi:[0,1]
	v_pk_fma_f32 v[18:19], v[32:33], v[32:33], v[2:3] op_sel_hi:[1,1,0]
	v_fmamk_f32 v29, v22, 0xbc000000, v29
	v_fmac_f32_e32 v28, 0xbc000000, v22
	v_fmamk_f32 v31, v22, 0xbc000000, v31
	v_fmac_f32_e32 v30, 0xbc000000, v22
	v_mul_f32_e32 v14, v30, v30
	v_mul_f32_e32 v18, v31, v31
	v_mul_f32_e32 v4, v28, v28
	v_mul_f32_e32 v2, v29, v29
	v_pk_add_f32 v[14:15], v[14:15], v[18:19]
	v_pk_add_f32 v[2:3], v[4:5], v[2:3]
	v_fmamk_f32 v27, v22, 0xbc000000, v27
	v_pk_add_f32 v[2:3], v[14:15], v[2:3]
	v_fmac_f32_e32 v26, 0xbc000000, v22
	v_fmamk_f32 v17, v22, 0xbc000000, v17
	v_fmac_f32_e32 v16, 0xbc000000, v22
	v_pk_add_f32 v[2:3], v[2:3], v[2:3] op_sel_hi:[0,1]
	v_pk_mul_f32 v[4:5], v[16:17], v[16:17]
	v_pk_mul_f32 v[14:15], v[26:27], v[26:27]
	v_fmac_f32_e32 v12, 0xbc000000, v22
	v_pk_mov_b32 v[18:19], v[14:15], v[4:5] op_sel:[1,0]
	v_mov_b32_e32 v15, v5
	v_fmac_f32_e32 v10, 0xbc000000, v22
	v_fmamk_f32 v13, v22, 0xbc000000, v13
	v_mul_f32_e32 v2, v12, v12
	v_pk_add_f32 v[4:5], v[18:19], v[14:15]
	v_fmamk_f32 v11, v22, 0xbc000000, v11
	v_pk_fma_f32 v[14:15], v[12:13], v[12:13], v[2:3] op_sel_hi:[1,1,0]
	v_mul_f32_e32 v2, v10, v10
	v_pk_add_f32 v[4:5], v[4:5], v[4:5] op_sel_hi:[0,1]
	v_pk_fma_f32 v[18:19], v[10:11], v[10:11], v[2:3] op_sel_hi:[1,1,0]
	v_fmamk_f32 v7, v22, 0xbc000000, v7
	v_fmac_f32_e32 v6, 0xbc000000, v22
	v_fmamk_f32 v9, v22, 0xbc000000, v9
	v_fmac_f32_e32 v8, 0xbc000000, v22
	v_mul_f32_e32 v14, v8, v8
	v_mul_f32_e32 v18, v9, v9
	v_mul_f32_e32 v4, v6, v6
	v_mul_f32_e32 v2, v7, v7
	v_pk_add_f32 v[14:15], v[14:15], v[18:19]
	v_pk_add_f32 v[2:3], v[4:5], v[2:3]
	s_nop 0
	v_pk_add_f32 v[2:3], v[14:15], v[2:3]
	s_nop 0
	v_add_f32_e32 v2, v2, v3
	ds_bpermute_b32 v3, v20, v2
	s_waitcnt lgkmcnt(0)
	v_add_f32_e32 v2, v2, v3
	ds_bpermute_b32 v3, v21, v2
	s_waitcnt lgkmcnt(0)
	v_add_f32_e32 v2, v2, v3
	v_fmamk_f32 v2, v2, 0x3c000000, v236
	v_cmp_gt_f32_e32 vcc, s68, v2
	v_mul_f32_e32 v3, 0x4f800000, v2
	s_nop 0
	v_cndmask_b32_e32 v2, v2, v3, vcc
	v_sqrt_f32_e32 v3, v2
	s_nop 0
	v_add_u32_e32 v4, -1, v3
	v_fma_f32 v5, -v4, v3, v2
	v_cmp_ge_f32_e64 s[40:41], 0, v5
	v_add_u32_e32 v5, 1, v3
	s_nop 0
	v_cndmask_b32_e64 v4, v3, v4, s[40:41]
	v_fma_f32 v3, -v5, v3, v2
	v_cmp_lt_f32_e64 s[40:41], 0, v3
	s_nop 1
	v_cndmask_b32_e64 v3, v4, v5, s[40:41]
	v_mul_f32_e32 v4, 0x37800000, v3
	v_cndmask_b32_e32 v3, v3, v4, vcc
	v_cmp_class_f32_e32 vcc, v2, v234
	s_nop 1
	v_cndmask_b32_e32 v2, v3, v2, vcc
	v_div_scale_f32 v3, s[22:23], v2, v2, 1.0
	v_rcp_f32_e32 v4, v3
	s_nop 0
	v_fma_f32 v5, -v3, v4, 1.0
	v_fmac_f32_e32 v4, v5, v4
	v_div_scale_f32 v5, vcc, 1.0, v2, 1.0
	v_mul_f32_e32 v14, v5, v4
	v_fma_f32 v15, -v3, v14, v5
	v_fmac_f32_e32 v14, v15, v4
	v_fma_f32 v3, -v3, v14, v5
	v_div_fmas_f32 v3, v3, v4, v14
	v_lshl_add_u64 v[4:5], s[46:47], 0, v[66:67]
	v_div_fixup_f32 v14, v3, v2, 1.0
	v_mov_b64_e32 v[2:3], s[56:57]
	v_lshlrev_b64 v[4:5], 12, v[4:5]
	v_mad_i64_i32 v[2:3], s[22:23], v66, s61, v[2:3]
	v_lshl_add_u64 v[4:5], s[44:45], 0, v[4:5]
	v_lshl_add_u64 v[2:3], v[2:3], 0, v[0:1]
	s_mov_b64 s[22:23], 0x1200
	v_lshl_add_u64 v[4:5], v[4:5], 0, s[52:53]
	v_lshl_add_u64 v[20:21], v[2:3], 0, s[22:23]
	v_lshl_add_u64 v[22:23], v[4:5], 0, v[0:1]
	s_mov_b64 s[22:23], 0x29600000
	v_lshl_add_u64 v[18:19], v[22:23], 0, s[22:23]
	s_lshl_b64 s[22:23], s[50:51], 2
	v_add_co_u32_e32 v2, vcc, s62, v2
	s_add_u32 s40, s20, s22
	s_nop 0
	v_addc_co_u32_e32 v3, vcc, 0, v3, vcc
	s_addc_u32 s41, s35, s23
	global_load_dwordx2 v[120:121], v[2:3], off offset:512
	global_load_dwordx4 v[122:125], v69, s[40:41]
	global_load_dwordx2 v[126:127], v[20:21], off offset:32
	global_load_dwordx4 v[128:131], v69, s[40:41] offset:64
	global_load_dwordx2 v[132:133], v[20:21], off offset:64
	global_load_dwordx4 v[134:137], v69, s[40:41] offset:128
	global_load_dwordx2 v[138:139], v[20:21], off offset:96
	global_load_dwordx4 v[140:143], v69, s[40:41] offset:192
	global_load_dwordx2 v[144:145], v[20:21], off offset:128
	global_load_dwordx4 v[146:149], v69, s[40:41] offset:256
	global_load_dwordx2 v[150:151], v[20:21], off offset:160
	global_load_dwordx4 v[152:155], v69, s[40:41] offset:320
	global_load_dwordx2 v[156:157], v[20:21], off offset:192
	global_load_dwordx4 v[158:161], v69, s[40:41] offset:384
	global_load_dwordx2 v[162:163], v[20:21], off offset:224
	global_load_dwordx4 v[164:167], v69, s[40:41] offset:448
	s_nop 0
	s_mov_b32 s20, 0x29600000
	s_waitcnt vmcnt(0)
; __device__ __forceinline__ unsigned pk2(float lo, float hi) { return pg8::cvt_pk_bf16(lo, hi); }
; __device__ __forceinline__ float silu_f(float g) { return g * frcp(1.f + fexp2(-LOG2E * g)); }
; __device__ __forceinline__ void ret_unit(LAS unsigned char* lds, const bfu* PROJ, const bfu* RT, const float* gn_g, bfu* CAT, int u) {
;     ...
;     for (int t = 0; t < 8; ++t) { const v2u gw = *(const v2u*)(gp + 16 * t); const f32x4 g4 = *(const f32x4*)(gg + 16 * t);
;         const float o0 = silu_f(bflo(gw.x)) * acc[t][0] * rstd * g4.x, o1 = silu_f(bfhi(gw.x)) * acc[t][1] * rstd * g4.y, o2 = silu_f(bflo(gw.y)) * acc[t][2] * rstd * g4.z, o3 = silu_f(bfhi(gw.y)) * acc[t][3] * rstd * g4.w;
;         v2u w; w.x = pk2(o0, o1); w.y = pk2(o2, o3); *(v2u*)(op + 16 * t) = w; }
	v_lshlrev_b32_e32 v48, 16, v120
	v_mul_f32_e32 v0, 0xbfb8aa3b, v48
	v_exp_f32_e32 v0, v0
	v_and_b32_e32 v49, 0xffff0000, v120
	v_lshlrev_b32_e32 v24, 16, v121
	v_and_b32_e32 v25, 0xffff0000, v121
	v_add_f32_e32 v0, 1.0, v0
	v_rcp_f32_e32 v50, v0
	v_mul_f32_e32 v0, 0xbfb8aa3b, v49
	v_exp_f32_e32 v0, v0
	s_nop 0
	v_add_f32_e32 v0, 1.0, v0
	v_rcp_f32_e32 v51, v0
	v_mul_f32_e32 v0, 0xbfb8aa3b, v24
	v_exp_f32_e32 v0, v0
	v_pk_mul_f32 v[48:49], v[50:51], v[48:49]
	s_nop 0
	v_pk_mul_f32 v[46:47], v[46:47], v[48:49]
	v_add_f32_e32 v0, 1.0, v0
	v_pk_mul_f32 v[46:47], v[46:47], v[14:15] op_sel_hi:[1,0]
	v_pk_mul_f32 v[2:3], v[122:123], v[46:47]
	v_rcp_f32_e32 v46, v0
	v_mul_f32_e32 v0, 0xbfb8aa3b, v25
	v_exp_f32_e32 v0, v0
	v_cvt_pk_bf16_f32 v2, v2, v3
	v_add_f32_e32 v0, 1.0, v0
	v_rcp_f32_e32 v47, v0
	s_nop 0
	v_pk_mul_f32 v[24:25], v[46:47], v[24:25]
	s_nop 0
	v_pk_mul_f32 v[24:25], v[44:45], v[24:25]
	s_nop 0
	v_pk_mul_f32 v[24:25], v[24:25], v[14:15] op_sel_hi:[1,0]
	s_nop 0
	v_pk_mul_f32 v[4:5], v[124:125], v[24:25]
	s_nop 0
	v_cvt_pk_bf16_f32 v3, v4, v5
	v_add_co_u32_e32 v4, vcc, s20, v22
	s_nop 1
	v_addc_co_u32_e32 v5, vcc, 0, v23, vcc
	global_store_dwordx2 v[4:5], v[2:3], off
	s_nop 0
	v_lshlrev_b32_e32 v24, 16, v126
	v_mul_f32_e32 v0, 0xbfb8aa3b, v24
	v_exp_f32_e32 v0, v0
	v_and_b32_e32 v25, 0xffff0000, v126
	v_lshlrev_b32_e32 v22, 16, v127
	v_and_b32_e32 v23, 0xffff0000, v127
	v_add_f32_e32 v0, 1.0, v0
	v_rcp_f32_e32 v44, v0
	v_mul_f32_e32 v0, 0xbfb8aa3b, v25
	v_exp_f32_e32 v0, v0
	s_nop 0
	v_add_f32_e32 v0, 1.0, v0
	v_rcp_f32_e32 v45, v0
	v_mul_f32_e32 v0, 0xbfb8aa3b, v22
	v_exp_f32_e32 v0, v0
	v_pk_mul_f32 v[24:25], v[44:45], v[24:25]
	s_nop 0
	v_pk_mul_f32 v[24:25], v[42:43], v[24:25]
	v_add_f32_e32 v0, 1.0, v0
	v_pk_mul_f32 v[24:25], v[24:25], v[14:15] op_sel_hi:[1,0]
	v_pk_mul_f32 v[2:3], v[128:129], v[24:25]
	v_rcp_f32_e32 v24, v0
	v_mul_f32_e32 v0, 0xbfb8aa3b, v23
	v_exp_f32_e32 v0, v0
	v_cvt_pk_bf16_f32 v2, v2, v3
	v_add_f32_e32 v0, 1.0, v0
	v_rcp_f32_e32 v25, v0
	s_nop 0
	v_pk_mul_f32 v[22:23], v[24:25], v[22:23]
	s_nop 0
	v_pk_mul_f32 v[22:23], v[40:41], v[22:23]
	s_nop 0
	v_pk_mul_f32 v[22:23], v[22:23], v[14:15] op_sel_hi:[1,0]
	s_nop 0
	v_pk_mul_f32 v[4:5], v[130:131], v[22:23]
	s_nop 0
	v_cvt_pk_bf16_f32 v3, v4, v5
	global_store_dwordx2 v[18:19], v[2:3], off offset:32
	s_nop 0
	v_lshlrev_b32_e32 v24, 16, v132
	v_mul_f32_e32 v0, 0xbfb8aa3b, v24
	v_exp_f32_e32 v0, v0
	v_and_b32_e32 v25, 0xffff0000, v132
	v_lshlrev_b32_e32 v22, 16, v133
	v_and_b32_e32 v23, 0xffff0000, v133
	v_add_f32_e32 v0, 1.0, v0
	v_rcp_f32_e32 v40, v0
	v_mul_f32_e32 v0, 0xbfb8aa3b, v25
	v_exp_f32_e32 v0, v0
	s_nop 0
	v_add_f32_e32 v0, 1.0, v0
	v_rcp_f32_e32 v41, v0
	v_mul_f32_e32 v0, 0xbfb8aa3b, v22
	v_exp_f32_e32 v0, v0
	v_pk_mul_f32 v[24:25], v[40:41], v[24:25]
	s_nop 0
	v_pk_mul_f32 v[24:25], v[38:39], v[24:25]
	v_add_f32_e32 v0, 1.0, v0
	v_pk_mul_f32 v[24:25], v[24:25], v[14:15] op_sel_hi:[1,0]
	v_pk_mul_f32 v[2:3], v[134:135], v[24:25]
	v_rcp_f32_e32 v24, v0
	v_mul_f32_e32 v0, 0xbfb8aa3b, v23
	v_exp_f32_e32 v0, v0
	v_cvt_pk_bf16_f32 v2, v2, v3
	v_add_f32_e32 v0, 1.0, v0
	v_rcp_f32_e32 v25, v0
	s_nop 0
	v_pk_mul_f32 v[22:23], v[24:25], v[22:23]
	s_nop 0
	v_pk_mul_f32 v[22:23], v[36:37], v[22:23]
	s_nop 0
	v_pk_mul_f32 v[22:23], v[22:23], v[14:15] op_sel_hi:[1,0]
	s_nop 0
	v_pk_mul_f32 v[4:5], v[136:137], v[22:23]
	s_nop 0
	v_cvt_pk_bf16_f32 v3, v4, v5
	global_store_dwordx2 v[18:19], v[2:3], off offset:64
	s_nop 0
	v_lshlrev_b32_e32 v24, 16, v138
	v_mul_f32_e32 v0, 0xbfb8aa3b, v24
	v_exp_f32_e32 v0, v0
	v_and_b32_e32 v25, 0xffff0000, v138
	v_lshlrev_b32_e32 v22, 16, v139
	v_and_b32_e32 v23, 0xffff0000, v139
	v_add_f32_e32 v0, 1.0, v0
	v_rcp_f32_e32 v36, v0
	v_mul_f32_e32 v0, 0xbfb8aa3b, v25
	v_exp_f32_e32 v0, v0
	s_nop 0
	v_add_f32_e32 v0, 1.0, v0
	v_rcp_f32_e32 v37, v0
	v_mul_f32_e32 v0, 0xbfb8aa3b, v22
	v_exp_f32_e32 v0, v0
	v_pk_mul_f32 v[24:25], v[36:37], v[24:25]
	s_nop 0
	v_pk_mul_f32 v[24:25], v[34:35], v[24:25]
	v_add_f32_e32 v0, 1.0, v0
	v_pk_mul_f32 v[24:25], v[24:25], v[14:15] op_sel_hi:[1,0]
	v_pk_mul_f32 v[2:3], v[140:141], v[24:25]
	v_rcp_f32_e32 v24, v0
	v_mul_f32_e32 v0, 0xbfb8aa3b, v23
	v_exp_f32_e32 v0, v0
	v_cvt_pk_bf16_f32 v2, v2, v3
	v_add_f32_e32 v0, 1.0, v0
	v_rcp_f32_e32 v25, v0
	s_nop 0
	v_pk_mul_f32 v[22:23], v[24:25], v[22:23]
	s_nop 0
	v_pk_mul_f32 v[22:23], v[32:33], v[22:23]
	s_nop 0
	v_pk_mul_f32 v[22:23], v[22:23], v[14:15] op_sel_hi:[1,0]
	s_nop 0
	v_pk_mul_f32 v[4:5], v[142:143], v[22:23]
	s_nop 0
	v_cvt_pk_bf16_f32 v3, v4, v5
	global_store_dwordx2 v[18:19], v[2:3], off offset:96
; __device__ __forceinline__ unsigned pk2(float lo, float hi) { return pg8::cvt_pk_bf16(lo, hi); }
; __device__ __forceinline__ float silu_f(float g) { return g * frcp(1.f + fexp2(-LOG2E * g)); }
; __device__ __forceinline__ void ret_unit(LAS unsigned char* lds, const bfu* PROJ, const bfu* RT, const float* gn_g, bfu* CAT, int u) {
;     ...
;     for (int t = 0; t < 8; ++t) { const v2u gw = *(const v2u*)(gp + 16 * t); const f32x4 g4 = *(const f32x4*)(gg + 16 * t);
;         const float o0 = silu_f(bflo(gw.x)) * acc[t][0] * rstd * g4.x, o1 = silu_f(bfhi(gw.x)) * acc[t][1] * rstd * g4.y, o2 = silu_f(bflo(gw.y)) * acc[t][2] * rstd * g4.z, o3 = silu_f(bfhi(gw.y)) * acc[t][3] * rstd * g4.w;
;         v2u w; w.x = pk2(o0, o1); w.y = pk2(o2, o3); *(v2u*)(op + 16 * t) = w; }
	s_nop 0
	v_lshlrev_b32_e32 v24, 16, v144
	v_mul_f32_e32 v0, 0xbfb8aa3b, v24
	v_exp_f32_e32 v0, v0
	v_and_b32_e32 v25, 0xffff0000, v144
	v_lshlrev_b32_e32 v22, 16, v145
	v_and_b32_e32 v23, 0xffff0000, v145
	v_add_f32_e32 v0, 1.0, v0
	v_rcp_f32_e32 v32, v0
	v_mul_f32_e32 v0, 0xbfb8aa3b, v25
	v_exp_f32_e32 v0, v0
	s_nop 0
	v_add_f32_e32 v0, 1.0, v0
	v_rcp_f32_e32 v33, v0
	v_mul_f32_e32 v0, 0xbfb8aa3b, v22
	v_exp_f32_e32 v0, v0
	v_pk_mul_f32 v[24:25], v[32:33], v[24:25]
	s_nop 0
	v_pk_mul_f32 v[24:25], v[30:31], v[24:25]
	v_add_f32_e32 v0, 1.0, v0
	v_pk_mul_f32 v[24:25], v[24:25], v[14:15] op_sel_hi:[1,0]
	v_pk_mul_f32 v[2:3], v[146:147], v[24:25]
	v_rcp_f32_e32 v24, v0
	v_mul_f32_e32 v0, 0xbfb8aa3b, v23
	v_exp_f32_e32 v0, v0
	v_cvt_pk_bf16_f32 v2, v2, v3
	v_add_f32_e32 v0, 1.0, v0
	v_rcp_f32_e32 v25, v0
	s_nop 0
	v_pk_mul_f32 v[22:23], v[24:25], v[22:23]
	s_nop 0
	v_pk_mul_f32 v[22:23], v[28:29], v[22:23]
	s_nop 0
	v_pk_mul_f32 v[22:23], v[22:23], v[14:15] op_sel_hi:[1,0]
	s_nop 0
	v_pk_mul_f32 v[4:5], v[148:149], v[22:23]
	s_nop 0
	v_cvt_pk_bf16_f32 v3, v4, v5
	global_store_dwordx2 v[18:19], v[2:3], off offset:128
	s_nop 0
	v_lshlrev_b32_e32 v24, 16, v150
	v_mul_f32_e32 v0, 0xbfb8aa3b, v24
	v_exp_f32_e32 v0, v0
	v_and_b32_e32 v25, 0xffff0000, v150
	v_lshlrev_b32_e32 v22, 16, v151
	v_and_b32_e32 v23, 0xffff0000, v151
	v_add_f32_e32 v0, 1.0, v0
	v_rcp_f32_e32 v28, v0
	v_mul_f32_e32 v0, 0xbfb8aa3b, v25
	v_exp_f32_e32 v0, v0
	s_nop 0
	v_add_f32_e32 v0, 1.0, v0
	v_rcp_f32_e32 v29, v0
	v_mul_f32_e32 v0, 0xbfb8aa3b, v22
	v_exp_f32_e32 v0, v0
	v_pk_mul_f32 v[24:25], v[28:29], v[24:25]
	s_nop 0
	v_pk_mul_f32 v[24:25], v[26:27], v[24:25]
	v_add_f32_e32 v0, 1.0, v0
	v_pk_mul_f32 v[24:25], v[14:15], v[24:25] op_sel_hi:[0,1]
	v_pk_mul_f32 v[2:3], v[152:153], v[24:25]
	v_rcp_f32_e32 v24, v0
	v_mul_f32_e32 v0, 0xbfb8aa3b, v23
	v_exp_f32_e32 v0, v0
	v_cvt_pk_bf16_f32 v2, v2, v3
	v_add_f32_e32 v0, 1.0, v0
	v_rcp_f32_e32 v25, v0
	s_nop 0
	v_pk_mul_f32 v[22:23], v[24:25], v[22:23]
	s_nop 0
	v_pk_mul_f32 v[16:17], v[16:17], v[22:23]
	s_nop 0
	v_pk_mul_f32 v[16:17], v[14:15], v[16:17] op_sel_hi:[0,1]
	v_pk_mul_f32 v[4:5], v[154:155], v[16:17]
	s_nop 0
	v_cvt_pk_bf16_f32 v3, v4, v5
	global_store_dwordx2 v[18:19], v[2:3], off offset:160
	s_nop 0
	v_lshlrev_b32_e32 v22, 16, v156
	v_mul_f32_e32 v0, 0xbfb8aa3b, v22
	v_exp_f32_e32 v0, v0
	v_and_b32_e32 v23, 0xffff0000, v156
	v_add_f32_e32 v0, 1.0, v0
	v_rcp_f32_e32 v24, v0
	v_mul_f32_e32 v0, 0xbfb8aa3b, v23
	v_exp_f32_e32 v0, v0
	s_nop 0
	v_add_f32_e32 v0, 1.0, v0
	v_rcp_f32_e32 v25, v0
	s_nop 0
	v_pk_mul_f32 v[22:23], v[24:25], v[22:23]
	s_nop 0
	v_pk_mul_f32 v[12:13], v[12:13], v[22:23]
	s_nop 0
	v_pk_mul_f32 v[12:13], v[14:15], v[12:13] op_sel_hi:[0,1]
	v_pk_mul_f32 v[2:3], v[158:159], v[12:13]
	v_lshlrev_b32_e32 v12, 16, v157
	v_mul_f32_e32 v0, 0xbfb8aa3b, v12
	v_exp_f32_e32 v0, v0
	v_and_b32_e32 v13, 0xffff0000, v157
	v_cvt_pk_bf16_f32 v2, v2, v3
	v_add_f32_e32 v0, 1.0, v0
	v_rcp_f32_e32 v16, v0
	v_mul_f32_e32 v0, 0xbfb8aa3b, v13
	v_exp_f32_e32 v0, v0
	s_nop 0
	v_add_f32_e32 v0, 1.0, v0
	v_rcp_f32_e32 v17, v0
	s_nop 0
	v_pk_mul_f32 v[12:13], v[16:17], v[12:13]
	s_nop 0
	v_pk_mul_f32 v[10:11], v[10:11], v[12:13]
	s_nop 0
	v_pk_mul_f32 v[10:11], v[14:15], v[10:11] op_sel_hi:[0,1]
	v_pk_mul_f32 v[4:5], v[160:161], v[10:11]
	s_nop 0
	v_cvt_pk_bf16_f32 v3, v4, v5
	global_store_dwordx2 v[18:19], v[2:3], off offset:192
	s_nop 0
	v_lshlrev_b32_e32 v12, 16, v162
	v_mul_f32_e32 v0, 0xbfb8aa3b, v12
	v_exp_f32_e32 v0, v0
	v_and_b32_e32 v13, 0xffff0000, v162
	v_add_f32_e32 v0, 1.0, v0
	v_rcp_f32_e32 v16, v0
	v_mul_f32_e32 v0, 0xbfb8aa3b, v13
	v_exp_f32_e32 v0, v0
	s_nop 0
	v_add_f32_e32 v0, 1.0, v0
	v_rcp_f32_e32 v17, v0
	s_nop 0
	v_pk_mul_f32 v[12:13], v[16:17], v[12:13]
	s_nop 0
	v_pk_mul_f32 v[8:9], v[8:9], v[12:13]
	s_nop 0
	v_pk_mul_f32 v[8:9], v[14:15], v[8:9] op_sel_hi:[0,1]
	v_pk_mul_f32 v[2:3], v[164:165], v[8:9]
	v_lshlrev_b32_e32 v8, 16, v163
	v_mul_f32_e32 v0, 0xbfb8aa3b, v8
	v_exp_f32_e32 v0, v0
	v_and_b32_e32 v9, 0xffff0000, v163
	v_cvt_pk_bf16_f32 v2, v2, v3
	v_add_f32_e32 v0, 1.0, v0
	v_rcp_f32_e32 v10, v0
	v_mul_f32_e32 v0, 0xbfb8aa3b, v9
	v_exp_f32_e32 v0, v0
	s_nop 0
	v_add_f32_e32 v0, 1.0, v0
	v_rcp_f32_e32 v11, v0
	s_nop 0
	v_pk_mul_f32 v[8:9], v[10:11], v[8:9]
	s_nop 0
	v_pk_mul_f32 v[6:7], v[6:7], v[8:9]
	s_nop 0
	v_pk_mul_f32 v[6:7], v[14:15], v[6:7] op_sel_hi:[0,1]
	v_pk_mul_f32 v[4:5], v[166:167], v[6:7]
	s_nop 0
	v_cvt_pk_bf16_f32 v3, v4, v5
	global_store_dwordx2 v[18:19], v[2:3], off offset:224
	s_barrier

; #define LAS __attribute__((address_space(3)))
; __device__ __forceinline__ float gelu_tanh(float x) { const float z = 0.7978845608028654f * (x + 0.044715f * x * x * x); return x * frcp(1.f + fexp2(-2.f * LOG2E * z)); }
; __device__ __forceinline__ void sgu_unit(LAS unsigned char* lds, const bfu* PROJ, const bfu* SW  , const float* ln_g, const float* ln_b, const float* sb, bfu* CAT, int s) {
;     int tid = threadIdx.x; asm volatile("" : "+v"(tid)); const int lane = tid & 63, wid = __builtin_amdgcn_readfirstlane(tid >> 6); (void)lane; (void)wid;
;     const int chunk = s >> 2, g = s & 3; const size_t row0 = (size_t)chunk * 128;
;     LAS bfu* Ws = (LAS bfu*)lds; LAS bfu* Vt = (LAS bfu*)(lds + TILE_B); LAS float* red = (LAS float*)(lds + 2 * TILE_B);
;     stage_nat(Ws, SW + (size_t)g * 16384, 128, tid);
;     const int sr = tid & 127, qd = tid >> 7;
;     const bfu* vp = PROJ + (row0 + sr) * INW + C_SV + g * 128 + qd * 32; float v[32]; float a = 0.f, a2 = 0.f;
; #pragma unroll
;     for (int k = 0; k < 4; ++k) { const v4u w = *(const v4u*)(vp + 8 * k);
; #pragma unroll
;         for (int j = 0; j < 4; ++j) { const float x0 = gelu_tanh(bflo(w[j])), x1 = gelu_tanh(bfhi(w[j])); v[8 * k + 2 * j] = x0; v[8 * k + 2 * j + 1] = x1; a += x0 + x1; a2 += x0 * x0 + x1 * x1; } }
.LBB0_422:
	s_mov_b32 s22, 21
	s_ashr_i32 s23, s22, 31
	s_lshl_b64 s[22:23], s[22:23], 3
	s_add_u32 s22, s0, s22
	s_addc_u32 s23, s1, s23
	s_load_dwordx2 s[22:23], s[22:23], 0x0
	s_mov_b32 s34, 21
	s_mov_b32 s46, 12
	s_mov_b32 s48, 21
	s_waitcnt lgkmcnt(0)
	s_add_u32 s44, s22, 0x1ce00000
	s_addc_u32 s45, s23, 0
	s_ashr_i32 s35, s34, 31
	s_lshl_b64 s[22:23], s[34:35], 3
	s_add_u32 s22, s0, s22
	s_addc_u32 s23, s1, s23
	s_load_dwordx2 s[22:23], s[22:23], 0x0
	s_mov_b32 s34, 9
	v_mov_b32_e32 v16, v232
	s_movk_i32 s56, 0x2000
	s_waitcnt lgkmcnt(0)
	s_add_u32 s20, s22, s55
	s_addc_u32 s53, s23, 0
	s_ashr_i32 s35, s34, 31
	s_lshl_b64 s[22:23], s[34:35], 3
	s_add_u32 s22, s0, s22
	s_addc_u32 s23, s1, s23
	s_load_dwordx2 s[22:23], s[22:23], 0x0
	s_mov_b32 s34, 10
	s_waitcnt lgkmcnt(0)
	s_add_u32 s22, s22, s26
	s_addc_u32 s23, s23, s27
	s_ashr_i32 s35, s34, 31
	s_lshl_b64 s[34:35], s[34:35], 3
	s_add_u32 s34, s0, s34
	s_addc_u32 s35, s1, s35
	s_load_dwordx2 s[40:41], s[34:35], 0x0
	s_waitcnt lgkmcnt(0)
	s_add_u32 s35, s40, s26
	s_addc_u32 s40, s41, s27
	s_ashr_i32 s47, s46, 31
	s_lshl_b64 s[46:47], s[46:47], 3
	s_add_u32 s46, s0, s46
	s_addc_u32 s47, s1, s47
	s_load_dwordx2 s[46:47], s[46:47], 0x0
	s_waitcnt lgkmcnt(0)
	s_add_u32 s50, s46, s26
	s_addc_u32 s51, s47, s27
	s_ashr_i32 s49, s48, 31
	s_lshl_b64 s[46:47], s[48:49], 3
	s_add_u32 s46, s0, s46
	s_addc_u32 s47, s1, s47
	s_lshl_b32 s41, s92, 5
	s_and_b32 s34, s92, 3
	s_and_b32 s41, s41, 0x3f80
	s_xor_b32 s52, s41, 0x2000
	s_lshl_b32 s41, s34, 15
	s_load_dwordx2 s[46:47], s[46:47], 0x0
	s_add_u32 s48, s20, s41
	v_lshlrev_b32_e32 v0, 4, v16
	s_addc_u32 s49, s53, 0
	v_and_b32_e32 v0, 0xf0, v0
	v_lshl_add_u64 v[2:3], s[48:49], 0, v[0:1]
	v_add_u32_e32 v4, 0, v0
	v_ashrrev_i32_e32 v6, 4, v16
	v_add_u32_e32 v0, 0x200, v16
	s_mov_b64 s[48:49], 0x100000
	v_ashrrev_i32_e32 v7, 31, v6
	v_ashrrev_i32_e32 v10, 4, v0
	v_lshl_add_u64 v[2:3], v[2:3], 0, s[48:49]
	v_lshlrev_b64 v[8:9], 8, v[6:7]
	v_ashrrev_i32_e32 v11, 31, v10
	v_lshl_add_u64 v[8:9], v[2:3], 0, v[8:9]
	v_lshlrev_b64 v[12:13], 8, v[10:11]
	v_add_u32_e32 v0, 0x400, v16
	v_lshl_add_u64 v[12:13], v[2:3], 0, v[12:13]
	global_load_dwordx4 v[20:23], v[8:9], off
	global_load_dwordx4 v[24:27], v[12:13], off
	v_ashrrev_i32_e32 v8, 4, v0
	v_add_u32_e32 v0, 0x600, v16
	v_ashrrev_i32_e32 v36, 4, v0
	v_ashrrev_i32_e32 v9, 31, v8
	v_ashrrev_i32_e32 v37, 31, v36
	v_and_b32_e32 v18, 0x7f, v16
	v_lshlrev_b64 v[12:13], 8, v[8:9]
	v_lshlrev_b64 v[14:15], 8, v[36:37]
	v_or_b32_e32 v0, s52, v18
	v_lshl_add_u64 v[12:13], v[2:3], 0, v[12:13]
	v_lshl_add_u64 v[2:3], v[2:3], 0, v[14:15]
	v_mul_u32_u24_e32 v0, 0x3200, v0
	v_ashrrev_i32_e32 v17, 2, v16
	global_load_dwordx4 v[28:31], v[12:13], off
	global_load_dwordx4 v[32:35], v[2:3], off
	v_lshl_add_u64 v[2:3], s[44:45], 0, v[0:1]
	s_lshl_b32 s20, s34, 8
	v_and_b32_e32 v14, 0xffffffe0, v17
	v_lshl_add_u64 v[2:3], v[2:3], 0, s[20:21]
	v_ashrrev_i32_e32 v15, 31, v14
	v_lshl_add_u64 v[2:3], v[14:15], 1, v[2:3]
	v_add_co_u32_e32 v12, vcc, s56, v2
	v_mad_u64_u32 v[38:39], s[48:49], v6, s65, v[4:5]
	s_nop 0
	v_addc_co_u32_e32 v13, vcc, 0, v3, vcc
	global_load_dwordx4 v[40:43], v[12:13], off offset:3584
	v_mad_u64_u32 v[44:45], s[48:49], v10, s65, v[4:5]
	v_mad_u64_u32 v[46:47], s[48:49], v8, s65, v[4:5]
	v_mad_u64_u32 v[36:37], s[48:49], v36, s65, v[4:5]
	s_mov_b64 s[48:49], 0x2e00
	s_nop 0
	v_lshl_add_u64 v[10:11], v[2:3], 0, s[48:49]
	global_load_dwordx4 v[2:5], v[10:11], off offset:48
	global_load_dwordx4 v[6:9], v[10:11], off offset:32
	s_nop 0
	global_load_dwordx4 v[10:13], v[10:11], off offset:16
	s_lshl_b32 s41, s34, 9
	s_add_u32 s22, s22, s41
	s_addc_u32 s23, s23, 0
	s_mov_b32 s53, s21
	s_waitcnt vmcnt(0)
	ds_write_b128 v38, v[20:23]
	s_waitcnt vmcnt(6)
	ds_write_b128 v44, v[24:27]
	s_waitcnt vmcnt(5)
	ds_write_b128 v46, v[28:31]
	s_waitcnt vmcnt(4)
	ds_write_b128 v36, v[32:35]
	s_waitcnt vmcnt(3)
	v_and_b32_e32 v26, 0xffff0000, v40
	v_lshlrev_b32_e32 v25, 16, v40
	v_and_b32_e32 v31, 0xffff0000, v41
	v_mul_f32_e32 v19, 0x3d372713, v26
	v_lshlrev_b32_e32 v28, 16, v41
	v_mul_f32_e32 v0, 0x3d372713, v25
	v_mul_f32_e32 v21, 0x3d372713, v31
	v_mul_f32_e32 v19, v19, v26
	v_mul_f32_e32 v20, 0x3d372713, v28
	v_mul_f32_e32 v0, v0, v25
	v_mul_f32_e32 v21, v21, v31
	v_fma_f32 v19, v19, v26, v26
	v_mul_f32_e32 v20, v20, v28
	v_fma_f32 v0, v0, v25, v25
	v_fma_f32 v21, v21, v31, v31
	v_mul_f32_e32 v19, 0x3f4c422a, v19
	v_fma_f32 v20, v20, v28, v28
	v_mul_f32_e32 v0, 0x3f4c422a, v0
	v_mul_f32_e32 v21, 0x3f4c422a, v21
	v_mul_f32_e32 v19, 0xc038aa3b, v19
	v_mul_f32_e32 v20, 0x3f4c422a, v20
	v_mul_f32_e32 v0, 0xc038aa3b, v0
	v_mul_f32_e32 v21, 0xc038aa3b, v21
	v_exp_f32_e32 v19, v19
	v_mul_f32_e32 v20, 0xc038aa3b, v20
	v_exp_f32_e32 v0, v0
	v_exp_f32_e32 v21, v21
	v_exp_f32_e32 v20, v20
	v_add_f32_e32 v19, 1.0, v19
	v_add_f32_e32 v0, 1.0, v0
	v_add_f32_e32 v21, 1.0, v21
	v_rcp_f32_e32 v40, v19
	v_add_f32_e32 v20, 1.0, v20
	v_rcp_f32_e32 v41, v0
	v_rcp_f32_e32 v35, v21
	v_rcp_f32_e32 v38, v20
	v_mul_f32_e32 v19, v40, v26
	v_mul_f32_e32 v0, v41, v25
	v_mul_f32_e32 v21, v35, v31
	v_fma_f32 v20, v41, v25, v19
	v_mul_f32_e32 v24, v19, v19
	v_add_f32_e32 v19, 0, v20
	v_fmac_f32_e32 v24, v0, v0
	v_fma_f32 v0, v38, v28, v21
	v_add_f32_e32 v0, v0, v19
	v_lshlrev_b32_e32 v19, 16, v42
	v_mul_f32_e32 v20, 0x3d372713, v19
	v_mul_f32_e32 v20, v20, v19
	v_fma_f32 v20, v20, v19, v19
	v_mul_f32_e32 v20, 0x3f4c422a, v20
	v_mul_f32_e32 v20, 0xc038aa3b, v20
	v_exp_f32_e32 v22, v20
	v_and_b32_e32 v20, 0xffff0000, v42
	v_mul_f32_e32 v27, 0x3d372713, v20
	v_mul_f32_e32 v27, v27, v20
	v_fma_f32 v27, v27, v20, v20
	v_mul_f32_e32 v27, 0x3f4c422a, v27
	v_mul_f32_e32 v27, 0xc038aa3b, v27
	v_exp_f32_e32 v27, v27
	v_mul_f32_e32 v29, v21, v21
	v_add_f32_e32 v21, 1.0, v22
	v_rcp_f32_e32 v22, v21
	v_add_f32_e32 v21, 1.0, v27
	v_rcp_f32_e32 v21, v21
	v_mul_f32_e32 v23, v38, v28
	v_fmac_f32_e32 v29, v23, v23
	v_add_f32_e32 v30, v24, v29
	v_mul_f32_e32 v27, v21, v20
	v_fma_f32 v23, v22, v19, v27
	v_add_f32_e32 v0, v23, v0
	v_lshlrev_b32_e32 v23, 16, v43
	v_mul_f32_e32 v24, 0x3d372713, v23
	v_mul_f32_e32 v24, v24, v23
	v_fma_f32 v24, v24, v23, v23
	v_mul_f32_e32 v24, 0x3f4c422a, v24
	v_mul_f32_e32 v24, 0xc038aa3b, v24
	v_exp_f32_e32 v29, v24
	v_and_b32_e32 v24, 0xffff0000, v43
	v_mul_f32_e32 v33, 0x3d372713, v24
	v_mul_f32_e32 v33, v33, v24
	v_fma_f32 v33, v33, v24, v24
	v_mul_f32_e32 v33, 0x3f4c422a, v33
	v_mul_f32_e32 v33, 0xc038aa3b, v33
	v_exp_f32_e32 v33, v33
	v_mul_f32_e32 v34, v27, v27
	v_add_f32_e32 v27, 1.0, v29
	v_rcp_f32_e32 v29, v27
	v_add_f32_e32 v27, 1.0, v33
	v_rcp_f32_e32 v27, v27
	v_mul_f32_e32 v32, v22, v19
	v_fmac_f32_e32 v34, v32, v32
	v_add_f32_e32 v34, v34, v30
	v_mul_f32_e32 v32, v27, v24
	v_fma_f32 v30, v29, v23, v32
	v_add_f32_e32 v0, v30, v0
	s_waitcnt vmcnt(0)
; __device__ __forceinline__ float gelu_tanh(float x) { const float z = 0.7978845608028654f * (x + 0.044715f * x * x * x); return x * frcp(1.f + fexp2(-2.f * LOG2E * z)); }
; __device__ __forceinline__ void sgu_unit(LAS unsigned char* lds, const bfu* PROJ, const bfu* SW  , const float* ln_g, const float* ln_b, const float* sb, bfu* CAT, int s) {
;     ...
;     for (int k = 0; k < 4; ++k) { const v4u w = *(const v4u*)(vp + 8 * k);
; #pragma unroll
;         for (int j = 0; j < 4; ++j) { const float x0 = gelu_tanh(bflo(w[j])), x1 = gelu_tanh(bfhi(w[j])); v[8 * k + 2 * j] = x0; v[8 * k + 2 * j + 1] = x1; a += x0 + x1; a2 += x0 * x0 + x1 * x1; } }
	v_lshlrev_b32_e32 v30, 16, v10
	v_mul_f32_e32 v33, 0x3d372713, v30
	v_and_b32_e32 v10, 0xffff0000, v10
	v_mul_f32_e32 v33, v33, v30
	v_mul_f32_e32 v37, 0x3d372713, v10
	v_fma_f32 v33, v33, v30, v30
	v_mul_f32_e32 v37, v37, v10
	v_mul_f32_e32 v33, 0x3f4c422a, v33
	v_fma_f32 v37, v37, v10, v10
	v_mul_f32_e32 v33, 0xc038aa3b, v33
	v_mul_f32_e32 v37, 0x3f4c422a, v37
	v_exp_f32_e32 v33, v33
	v_mul_f32_e32 v37, 0xc038aa3b, v37
	v_exp_f32_e32 v37, v37
	v_mul_f32_e32 v39, v32, v32
	v_add_f32_e32 v32, 1.0, v33
	v_rcp_f32_e32 v33, v32
	v_add_f32_e32 v32, 1.0, v37
	v_rcp_f32_e32 v32, v32
	v_mul_f32_e32 v36, v29, v23
	v_fmac_f32_e32 v39, v36, v36
	v_add_f32_e32 v37, v39, v34
	v_mul_f32_e32 v36, v32, v10
	v_fma_f32 v34, v33, v30, v36
	v_add_f32_e32 v0, v34, v0
	v_lshlrev_b32_e32 v34, 16, v11
	v_mul_f32_e32 v39, 0x3d372713, v34
	v_and_b32_e32 v11, 0xffff0000, v11
	v_mul_f32_e32 v39, v39, v34
	v_mul_f32_e32 v43, 0x3d372713, v11
	v_fma_f32 v39, v39, v34, v34
	v_mul_f32_e32 v43, v43, v11
	v_mul_f32_e32 v39, 0x3f4c422a, v39
	v_fma_f32 v43, v43, v11, v11
	v_mul_f32_e32 v39, 0xc038aa3b, v39
	v_mul_f32_e32 v43, 0x3f4c422a, v43
	v_exp_f32_e32 v39, v39
	v_mul_f32_e32 v43, 0xc038aa3b, v43
	v_exp_f32_e32 v43, v43
	v_mul_f32_e32 v44, v36, v36
	v_add_f32_e32 v36, 1.0, v39
	v_rcp_f32_e32 v39, v36
	v_add_f32_e32 v36, 1.0, v43
	v_rcp_f32_e32 v36, v36
	v_mul_f32_e32 v42, v33, v30
	v_fmac_f32_e32 v44, v42, v42
	v_add_f32_e32 v44, v44, v37
	v_mul_f32_e32 v42, v36, v11
	v_fma_f32 v37, v39, v34, v42
	v_add_f32_e32 v0, v37, v0
	v_lshlrev_b32_e32 v37, 16, v12
	v_mul_f32_e32 v43, 0x3d372713, v37
	v_and_b32_e32 v12, 0xffff0000, v12
	v_mul_f32_e32 v43, v43, v37
	v_mul_f32_e32 v46, 0x3d372713, v12
	v_fma_f32 v43, v43, v37, v37
	v_mul_f32_e32 v46, v46, v12
	v_mul_f32_e32 v43, 0x3f4c422a, v43
	v_fma_f32 v46, v46, v12, v12
	v_mul_f32_e32 v43, 0xc038aa3b, v43
	v_mul_f32_e32 v46, 0x3f4c422a, v46
	v_exp_f32_e32 v43, v43
	v_mul_f32_e32 v46, 0xc038aa3b, v46
	v_exp_f32_e32 v46, v46
	v_mul_f32_e32 v47, v42, v42
	v_add_f32_e32 v42, 1.0, v43
	v_rcp_f32_e32 v43, v42
	v_add_f32_e32 v42, 1.0, v46
	v_rcp_f32_e32 v42, v42
	v_mul_f32_e32 v45, v39, v34
	v_fmac_f32_e32 v47, v45, v45
	v_add_f32_e32 v47, v47, v44
	v_mul_f32_e32 v45, v42, v12
	v_fma_f32 v44, v43, v37, v45
	v_add_f32_e32 v0, v44, v0
	v_lshlrev_b32_e32 v44, 16, v13
	v_mul_f32_e32 v46, 0x3d372713, v44
	v_and_b32_e32 v13, 0xffff0000, v13
	v_mul_f32_e32 v46, v46, v44
	v_mul_f32_e32 v49, 0x3d372713, v13
	v_fma_f32 v46, v46, v44, v44
	v_mul_f32_e32 v49, v49, v13
	v_mul_f32_e32 v46, 0x3f4c422a, v46
	v_fma_f32 v49, v49, v13, v13
	v_mul_f32_e32 v46, 0xc038aa3b, v46
	v_mul_f32_e32 v49, 0x3f4c422a, v49
	v_exp_f32_e32 v46, v46
	v_mul_f32_e32 v49, 0xc038aa3b, v49
	v_exp_f32_e32 v49, v49
	v_mul_f32_e32 v50, v45, v45
	v_add_f32_e32 v45, 1.0, v46
	v_rcp_f32_e32 v46, v45
	v_add_f32_e32 v45, 1.0, v49
	v_rcp_f32_e32 v45, v45
	v_mul_f32_e32 v48, v43, v37
	v_fmac_f32_e32 v50, v48, v48
	v_add_f32_e32 v50, v50, v47
	v_mul_f32_e32 v48, v45, v13
	v_fma_f32 v47, v46, v44, v48
	v_add_f32_e32 v0, v47, v0
	v_lshlrev_b32_e32 v47, 16, v6
	v_mul_f32_e32 v49, 0x3d372713, v47
	v_and_b32_e32 v6, 0xffff0000, v6
	v_mul_f32_e32 v49, v49, v47
	v_mul_f32_e32 v52, 0x3d372713, v6
	v_fma_f32 v49, v49, v47, v47
	v_mul_f32_e32 v52, v52, v6
	v_mul_f32_e32 v49, 0x3f4c422a, v49
	v_fma_f32 v52, v52, v6, v6
	v_mul_f32_e32 v49, 0xc038aa3b, v49
	v_mul_f32_e32 v52, 0x3f4c422a, v52
	v_exp_f32_e32 v49, v49
	v_mul_f32_e32 v52, 0xc038aa3b, v52
	v_exp_f32_e32 v52, v52
	v_mul_f32_e32 v53, v48, v48
	v_add_f32_e32 v48, 1.0, v49
	v_rcp_f32_e32 v49, v48
	v_add_f32_e32 v48, 1.0, v52
	v_rcp_f32_e32 v48, v48
	v_mul_f32_e32 v51, v46, v44
	v_fmac_f32_e32 v53, v51, v51
	v_add_f32_e32 v53, v53, v50
	v_mul_f32_e32 v51, v48, v6
	v_fma_f32 v50, v49, v47, v51
	v_add_f32_e32 v0, v50, v0
	v_lshlrev_b32_e32 v50, 16, v7
	v_mul_f32_e32 v52, 0x3d372713, v50
	v_and_b32_e32 v7, 0xffff0000, v7
	v_mul_f32_e32 v52, v52, v50
	v_mul_f32_e32 v55, 0x3d372713, v7
	v_fma_f32 v52, v52, v50, v50
	v_mul_f32_e32 v55, v55, v7
	v_mul_f32_e32 v52, 0x3f4c422a, v52
	v_fma_f32 v55, v55, v7, v7
	v_mul_f32_e32 v52, 0xc038aa3b, v52
	v_mul_f32_e32 v55, 0x3f4c422a, v55
	v_exp_f32_e32 v52, v52
	v_mul_f32_e32 v55, 0xc038aa3b, v55
	v_exp_f32_e32 v55, v55
	v_mul_f32_e32 v56, v51, v51
	v_add_f32_e32 v51, 1.0, v52
	v_rcp_f32_e32 v52, v51
	v_add_f32_e32 v51, 1.0, v55
	v_rcp_f32_e32 v51, v51
	v_mul_f32_e32 v54, v49, v47
	v_fmac_f32_e32 v56, v54, v54
	v_add_f32_e32 v56, v56, v53
	v_mul_f32_e32 v54, v51, v7
	v_fma_f32 v53, v52, v50, v54
	v_add_f32_e32 v0, v53, v0
	v_lshlrev_b32_e32 v53, 16, v8
	v_mul_f32_e32 v55, 0x3d372713, v53
	v_and_b32_e32 v8, 0xffff0000, v8
	v_mul_f32_e32 v55, v55, v53
	v_mul_f32_e32 v58, 0x3d372713, v8
	v_fma_f32 v55, v55, v53, v53
	v_mul_f32_e32 v58, v58, v8
	v_mul_f32_e32 v55, 0x3f4c422a, v55
	v_fma_f32 v58, v58, v8, v8
	v_mul_f32_e32 v55, 0xc038aa3b, v55
	v_mul_f32_e32 v58, 0x3f4c422a, v58
	v_exp_f32_e32 v55, v55
	v_mul_f32_e32 v58, 0xc038aa3b, v58
	v_exp_f32_e32 v58, v58
	v_mul_f32_e32 v59, v54, v54
	v_add_f32_e32 v54, 1.0, v55
	v_rcp_f32_e32 v55, v54
	v_add_f32_e32 v54, 1.0, v58
	v_rcp_f32_e32 v54, v54
	v_mul_f32_e32 v57, v52, v50
	v_fmac_f32_e32 v59, v57, v57
	v_add_f32_e32 v57, v59, v56
	v_mul_f32_e32 v59, v54, v8
	v_fma_f32 v56, v55, v53, v59
	v_add_f32_e32 v0, v56, v0
	v_lshlrev_b32_e32 v56, 16, v9
	v_mul_f32_e32 v60, 0x3d372713, v56
	v_and_b32_e32 v9, 0xffff0000, v9
	v_mul_f32_e32 v60, v60, v56
	v_mul_f32_e32 v61, 0x3d372713, v9
	v_fma_f32 v60, v60, v56, v56
	v_mul_f32_e32 v61, v61, v9
	v_mul_f32_e32 v60, 0x3f4c422a, v60
	v_fma_f32 v61, v61, v9, v9
	v_mul_f32_e32 v60, 0xc038aa3b, v60
	v_mul_f32_e32 v61, 0x3f4c422a, v61
; __device__ __forceinline__ float gelu_tanh(float x) { const float z = 0.7978845608028654f * (x + 0.044715f * x * x * x); return x * frcp(1.f + fexp2(-2.f * LOG2E * z)); }
; __device__ __forceinline__ void sgu_unit(LAS unsigned char* lds, const bfu* PROJ, const bfu* SW  , const float* ln_g, const float* ln_b, const float* sb, bfu* CAT, int s) {
;     ...
;         for (int j = 0; j < 4; ++j) { const float x0 = gelu_tanh(bflo(w[j])), x1 = gelu_tanh(bfhi(w[j])); v[8 * k + 2 * j] = x0; v[8 * k + 2 * j + 1] = x1; a += x0 + x1; a2 += x0 * x0 + x1 * x1; } }
;     red[qd * 128 + sr] = a; red[512 + qd * 128 + sr] = a2;
;     __syncthreads();
;     { const float sm = (red[sr] + red[128 + sr]) + (red[256 + sr] + red[384 + sr]), sq = (red[512 + sr] + red[640 + sr]) + (red[768 + sr] + red[896 + sr]);
;       const float mu = sm * (1.f / 128.f), var = fmaxf(sq * (1.f / 128.f) - mu * mu, 0.f), rstd = 1.f / sqrtf(var + EPS);
;       const float* lg_ = ln_g + g * 128 + qd * 32; const float* lb_ = ln_b + g * 128 + qd * 32;
	v_exp_f32_e32 v60, v60
	v_mul_f32_e32 v61, 0xc038aa3b, v61
	v_exp_f32_e32 v61, v61
	v_mul_f32_e32 v58, v55, v53
	v_add_f32_e32 v60, 1.0, v60
	v_rcp_f32_e32 v69, v60
	v_add_f32_e32 v60, 1.0, v61
	v_rcp_f32_e32 v102, v60
	v_mul_f32_e32 v59, v59, v59
	v_fmac_f32_e32 v59, v58, v58
	v_add_f32_e32 v57, v59, v57
	v_mul_f32_e32 v59, v102, v9
	v_and_b32_e32 v104, 0xffff0000, v2
	v_fma_f32 v60, v69, v56, v59
	v_lshlrev_b32_e32 v103, 16, v2
	v_mul_f32_e32 v2, 0x3d372713, v104
	v_add_f32_e32 v0, v60, v0
	v_mul_f32_e32 v60, 0x3d372713, v103
	v_mul_f32_e32 v2, v2, v104
	v_mul_f32_e32 v60, v60, v103
	v_fma_f32 v2, v2, v104, v104
	v_fma_f32 v60, v60, v103, v103
	v_mul_f32_e32 v2, 0x3f4c422a, v2
	v_mul_f32_e32 v60, 0x3f4c422a, v60
	v_mul_f32_e32 v2, 0xc038aa3b, v2
	v_mul_f32_e32 v60, 0xc038aa3b, v60
	v_exp_f32_e32 v2, v2
	v_exp_f32_e32 v60, v60
	v_mul_f32_e32 v58, v69, v56
	v_mul_f32_e32 v59, v59, v59
	v_add_f32_e32 v2, 1.0, v2
	v_add_f32_e32 v60, 1.0, v60
	v_rcp_f32_e32 v106, v2
	v_rcp_f32_e32 v105, v60
	v_fmac_f32_e32 v59, v58, v58
	v_and_b32_e32 v108, 0xffff0000, v3
	v_mul_f32_e32 v58, v106, v104
	v_add_f32_e32 v2, v59, v57
	v_fma_f32 v59, v105, v103, v58
	v_lshlrev_b32_e32 v107, 16, v3
	v_mul_f32_e32 v3, 0x3d372713, v108
	v_add_f32_e32 v0, v59, v0
	v_mul_f32_e32 v59, 0x3d372713, v107
	v_mul_f32_e32 v3, v3, v108
	v_mul_f32_e32 v59, v59, v107
	v_fma_f32 v3, v3, v108, v108
	v_fma_f32 v59, v59, v107, v107
	v_mul_f32_e32 v3, 0x3f4c422a, v3
	v_mul_f32_e32 v59, 0x3f4c422a, v59
	v_mul_f32_e32 v3, 0xc038aa3b, v3
	v_mul_f32_e32 v59, 0xc038aa3b, v59
	v_exp_f32_e32 v3, v3
	v_exp_f32_e32 v59, v59
	v_mul_f32_e32 v57, v105, v103
	v_mul_f32_e32 v58, v58, v58
	v_add_f32_e32 v3, 1.0, v3
	v_add_f32_e32 v59, 1.0, v59
	v_rcp_f32_e32 v110, v3
	v_rcp_f32_e32 v109, v59
	v_fmac_f32_e32 v58, v57, v57
	v_and_b32_e32 v112, 0xffff0000, v4
	v_mul_f32_e32 v57, v110, v108
	v_add_f32_e32 v2, v58, v2
	v_fma_f32 v58, v109, v107, v57
	v_lshlrev_b32_e32 v111, 16, v4
	v_mul_f32_e32 v4, 0x3d372713, v112
	v_add_f32_e32 v0, v58, v0
	v_mul_f32_e32 v58, 0x3d372713, v111
	v_mul_f32_e32 v4, v4, v112
	v_mul_f32_e32 v58, v58, v111
	v_fma_f32 v4, v4, v112, v112
	v_fma_f32 v58, v58, v111, v111
	v_mul_f32_e32 v4, 0x3f4c422a, v4
	v_mul_f32_e32 v58, 0x3f4c422a, v58
	v_mul_f32_e32 v4, 0xc038aa3b, v4
	v_mul_f32_e32 v58, 0xc038aa3b, v58
	v_exp_f32_e32 v4, v4
	v_exp_f32_e32 v58, v58
	v_mul_f32_e32 v3, v109, v107
	v_mul_f32_e32 v57, v57, v57
	v_add_f32_e32 v4, 1.0, v4
	v_add_f32_e32 v58, 1.0, v58
	v_rcp_f32_e32 v114, v4
	v_rcp_f32_e32 v113, v58
	v_fmac_f32_e32 v57, v3, v3
	v_add_f32_e32 v2, v57, v2
	v_mul_f32_e32 v4, v114, v112
	v_fma_f32 v57, v113, v111, v4
	v_and_b32_e32 v115, 0xffff0000, v5
	v_add_f32_e32 v0, v57, v0
	v_lshlrev_b32_e32 v57, 16, v5
	v_mul_f32_e32 v5, 0x3d372713, v115
	v_mul_f32_e32 v58, 0x3d372713, v57
	v_mul_f32_e32 v5, v5, v115
	v_mul_f32_e32 v58, v58, v57
	v_fma_f32 v5, v5, v115, v115
	v_fma_f32 v58, v58, v57, v57
	v_mul_f32_e32 v5, 0x3f4c422a, v5
	v_mul_f32_e32 v58, 0x3f4c422a, v58
	v_mul_f32_e32 v5, 0xc038aa3b, v5
	v_mul_f32_e32 v58, 0xc038aa3b, v58
	v_exp_f32_e32 v5, v5
	v_exp_f32_e32 v58, v58
	v_mul_f32_e32 v3, v113, v111
	v_mul_f32_e32 v4, v4, v4
	v_add_f32_e32 v5, 1.0, v5
	v_add_f32_e32 v58, 1.0, v58
	v_rcp_f32_e32 v117, v5
	v_rcp_f32_e32 v116, v58
	v_fmac_f32_e32 v4, v3, v3
	v_add_f32_e32 v2, v4, v2
	v_mul_f32_e32 v4, v117, v115
	v_mul_f32_e32 v3, v116, v57
	v_fma_f32 v5, v116, v57, v4
	v_mul_f32_e32 v4, v4, v4
	v_fmac_f32_e32 v4, v3, v3
	v_add_f32_e32 v0, v5, v0
	v_add_f32_e32 v2, v4, v2
	v_lshl_add_u32 v4, v16, 2, s70
	v_and_b32_e32 v3, 0x3fffff80, v16
	ds_write_b32 v4, v0
	v_lshl_add_u32 v0, v18, 2, s70
	v_lshl_add_u32 v3, v3, 2, v0
	ds_write_b32 v3, v2 offset:2048
	v_lshlrev_b64 v[2:3], 2, v[14:15]
	v_lshl_add_u64 v[4:5], s[22:23], 0, v[2:3]
	s_add_u32 s22, s35, s41
	s_addc_u32 s23, s40, 0
	v_lshl_add_u64 v[66:67], s[22:23], 0, v[2:3]
	s_waitcnt lgkmcnt(0)
	s_barrier
	global_load_dwordx4 v[58:61], v[66:67], off
	global_load_dwordx4 v[62:65], v[4:5], off
	global_load_dwordx4 v[70:73], v[4:5], off offset:16
	ds_read2st64_b32 v[2:3], v0 offset1:2
	ds_read2st64_b32 v[78:79], v0 offset0:4 offset1:6
	global_load_dwordx4 v[74:77], v[66:67], off offset:16
	ds_read2st64_b32 v[80:81], v0 offset0:8 offset1:10
	ds_read2st64_b32 v[82:83], v0 offset0:12 offset1:14
	s_brev_b32 s22, 60
	s_waitcnt lgkmcnt(3)
	v_add_f32_e32 v0, v2, v3
	s_waitcnt lgkmcnt(2)
	v_add_f32_e32 v2, v78, v79
	v_add_f32_e32 v0, v0, v2
	s_waitcnt lgkmcnt(1)
	v_add_f32_e32 v2, v80, v81
	s_waitcnt lgkmcnt(0)
	v_add_f32_e32 v3, v82, v83
	v_mul_f32_e32 v15, 0x3c000000, v0
	v_add_f32_e32 v2, v2, v3
	v_mul_f32_e32 v0, v15, v15
	v_fma_f32 v0, v2, s22, -v0
	v_max_f32_e32 v0, 0, v0
	v_add_f32_e32 v0, 0x358637bd, v0
	v_mul_f32_e32 v2, 0x4f800000, v0
	v_cmp_gt_f32_e32 vcc, s68, v0
	s_nop 1
	v_cndmask_b32_e32 v0, v0, v2, vcc
	v_sqrt_f32_e32 v2, v0
	s_nop 0
	v_add_u32_e32 v3, -1, v2
	v_fma_f32 v78, -v3, v2, v0
	v_cmp_ge_f32_e64 s[40:41], 0, v78
	global_load_dwordx4 v[78:81], v[4:5], off offset:32
	global_load_dwordx4 v[82:85], v[66:67], off offset:32
	v_add_u32_e32 v86, 1, v2
	v_cndmask_b32_e64 v3, v2, v3, s[40:41]
	v_fma_f32 v2, -v86, v2, v0
	v_cmp_lt_f32_e64 s[40:41], 0, v2
	s_nop 1
	v_cndmask_b32_e64 v2, v3, v86, s[40:41]
	v_mul_f32_e32 v3, 0x37800000, v2
	v_cndmask_b32_e32 v2, v2, v3, vcc
	v_cmp_class_f32_e32 vcc, v0, v234
	global_load_dwordx4 v[86:89], v[4:5], off offset:48
	global_load_dwordx4 v[90:93], v[66:67], off offset:48
	v_cndmask_b32_e32 v0, v2, v0, vcc
	v_div_scale_f32 v2, s[22:23], v0, v0, 1.0
	v_rcp_f32_e32 v3, v2
	v_readfirstlane_b32 s22, v16
	s_ashr_i32 s22, s22, 2
	v_fma_f32 v94, -v2, v3, 1.0
	v_fmac_f32_e32 v3, v94, v3
	v_div_scale_f32 v94, vcc, 1.0, v0, 1.0
	v_mul_f32_e32 v95, v94, v3
	v_fma_f32 v96, -v2, v95, v94
	v_fmac_f32_e32 v95, v96, v3
	v_fma_f32 v2, -v2, v95, v94
	v_div_fmas_f32 v2, v2, v3, v95
	v_div_fixup_f32 v118, v2, v0, 1.0
	v_fma_f32 v2, v41, v25, -v15
	v_mul_f32_e32 v2, v2, v118
	v_lshl_add_u32 v0, v18, 1, 0
	s_waitcnt vmcnt(6)
; __device__ __forceinline__ unsigned f2bf(float f) { unsigned u = __builtin_bit_cast(unsigned, f); return (u + 0x7fffu + ((u >> 16) & 1u)) >> 16; }
; #define ZERO8(a) do { _Pragma("unroll") for (int t_ = 0; t_ < 8; ++t_) a[t_] = (f32x4){0.f, 0.f, 0.f, 0.f}; } while (0)
; __device__ __forceinline__ void sgu_unit(LAS unsigned char* lds, const bfu* PROJ, const bfu* SW  , const float* ln_g, const float* ln_b, const float* sb, bfu* CAT, int s) {
;     ...
;       const float* lg_ = ln_g + g * 128 + qd * 32; const float* lb_ = ln_b + g * 128 + qd * 32;
; #pragma unroll
;       for (int k = 0; k < 32; ++k) Vt[(qd * 32 + k) * TS + sr] = (bfu)f2bf((v[k] - mu) * rstd * lg_[k] + lb_[k]); }
;     __syncthreads();
;     const int fr = lane & 15, fq = lane >> 4, m0 = wid * 16, t_ = m0 + fr; f32x4 acc[8]; ZERO8(acc);
;     wave_mma(acc, Ws, Vt, m0, fr, fq);
;     const float bias = sb[g * 128 + t_];
;     const bfu* up = PROJ + (row0 + t_) * INW + C_SU + g * 128 + 4 * fq; bfu* op = CAT + (row0 + t_) * DM + 1536 + g * 128 + 4 * fq;
	v_fma_f32 v2, v62, v2, v58
	v_bfe_u32 v3, v2, 16, 1
	v_add3_u32 v18, v2, v3, s71
	v_mad_u64_u32 v[2:3], s[40:41], v14, s65, v[0:1]
	v_fma_f32 v3, v40, v26, -v15
	v_mul_f32_e32 v3, v3, v118
	v_fma_f32 v3, v63, v3, v59
	v_bfe_u32 v14, v3, 16, 1
	v_add3_u32 v3, v3, v14, s71
	ds_write_b16_d16_hi v2, v3 offset:35088
	v_fma_f32 v3, v38, v28, -v15
	v_mul_f32_e32 v3, v3, v118
	v_fma_f32 v3, v64, v3, v60
	v_bfe_u32 v14, v3, 16, 1
	v_add3_u32 v3, v3, v14, s71
	ds_write_b16_d16_hi v2, v3 offset:35360
	v_fma_f32 v3, v35, v31, -v15
	v_mul_f32_e32 v3, v3, v118
	v_fmac_f32_e32 v61, v3, v65
	ds_write_b16_d16_hi v2, v18 offset:34816
	v_bfe_u32 v3, v61, 16, 1
	v_add3_u32 v3, v61, v3, s71
	global_load_dwordx4 v[58:61], v[4:5], off offset:80
	global_load_dwordx4 v[62:65], v[4:5], off offset:64
	global_load_dwordx4 v[94:97], v[66:67], off offset:80
	global_load_dwordx4 v[98:101], v[66:67], off offset:64
	ds_write_b16_d16_hi v2, v3 offset:35632
	v_fma_f32 v3, v22, v19, -v15
	v_mul_f32_e32 v3, v3, v118
	s_waitcnt vmcnt(8)
	v_fma_f32 v3, v3, v70, v74
	v_bfe_u32 v14, v3, 16, 1
	v_add3_u32 v3, v3, v14, s71
	ds_write_b16_d16_hi v2, v3 offset:35904
	v_fma_f32 v3, v21, v20, -v15
	v_mul_f32_e32 v3, v3, v118
	v_fma_f32 v3, v3, v71, v75
	v_bfe_u32 v14, v3, 16, 1
	v_add3_u32 v3, v3, v14, s71
	ds_write_b16_d16_hi v2, v3 offset:36176
	v_fma_f32 v3, v29, v23, -v15
	v_mul_f32_e32 v3, v3, v118
	v_fma_f32 v3, v3, v72, v76
	v_bfe_u32 v14, v3, 16, 1
	v_add3_u32 v3, v3, v14, s71
	ds_write_b16_d16_hi v2, v3 offset:36448
	v_fma_f32 v3, v27, v24, -v15
	v_mul_f32_e32 v3, v3, v118
	v_fmac_f32_e32 v77, v3, v73
	v_bfe_u32 v3, v77, 16, 1
	v_add3_u32 v3, v77, v3, s71
	ds_write_b16_d16_hi v2, v3 offset:36720
	v_fma_f32 v3, v33, v30, -v15
	v_mul_f32_e32 v3, v3, v118
	s_waitcnt vmcnt(6)
	v_fma_f32 v3, v3, v78, v82
	v_bfe_u32 v14, v3, 16, 1
	v_add3_u32 v3, v3, v14, s71
	ds_write_b16_d16_hi v2, v3 offset:36992
	v_fma_f32 v3, v32, v10, -v15
	v_mul_f32_e32 v3, v3, v118
	v_fma_f32 v3, v3, v79, v83
	v_bfe_u32 v10, v3, 16, 1
	v_add3_u32 v3, v3, v10, s71
	ds_write_b16_d16_hi v2, v3 offset:37264
	v_fma_f32 v3, v39, v34, -v15
	v_mul_f32_e32 v3, v3, v118
	v_fma_f32 v3, v3, v80, v84
	v_bfe_u32 v10, v3, 16, 1
	v_add3_u32 v3, v3, v10, s71
	ds_write_b16_d16_hi v2, v3 offset:37536
	global_load_dwordx4 v[18:21], v[4:5], off offset:112
	global_load_dwordx4 v[22:25], v[4:5], off offset:96
	global_load_dwordx4 v[26:29], v[66:67], off offset:112
	global_load_dwordx4 v[30:33], v[66:67], off offset:96
	v_fma_f32 v3, v36, v11, -v15
	v_mul_f32_e32 v3, v3, v118
	v_fmac_f32_e32 v85, v3, v81
	v_bfe_u32 v3, v85, 16, 1
	v_add3_u32 v3, v85, v3, s71
	ds_write_b16_d16_hi v2, v3 offset:37808
	v_fma_f32 v3, v43, v37, -v15
	v_mul_f32_e32 v3, v3, v118
	s_waitcnt vmcnt(8)
	v_fma_f32 v3, v3, v86, v90
	v_bfe_u32 v4, v3, 16, 1
	v_add3_u32 v3, v3, v4, s71
	ds_write_b16_d16_hi v2, v3 offset:38080
	v_fma_f32 v3, v42, v12, -v15
	v_mul_f32_e32 v3, v3, v118
	v_fma_f32 v3, v3, v87, v91
	v_bfe_u32 v4, v3, 16, 1
	v_add3_u32 v3, v3, v4, s71
	ds_write_b16_d16_hi v2, v3 offset:38352
	v_fma_f32 v3, v46, v44, -v15
	v_mul_f32_e32 v3, v3, v118
	v_fma_f32 v3, v3, v88, v92
	v_bfe_u32 v4, v3, 16, 1
	v_add3_u32 v3, v3, v4, s71
	ds_write_b16_d16_hi v2, v3 offset:38624
	v_fma_f32 v3, v45, v13, -v15
	v_mul_f32_e32 v3, v3, v118
	v_fmac_f32_e32 v93, v3, v89
	v_bfe_u32 v3, v93, 16, 1
	v_add3_u32 v3, v93, v3, s71
	ds_write_b16_d16_hi v2, v3 offset:38896
	v_fma_f32 v3, v49, v47, -v15
	v_mul_f32_e32 v3, v3, v118
	v_bfi_b32 v14, -16, s22, v16
	s_waitcnt vmcnt(4)
	v_fma_f32 v3, v3, v62, v98
	v_bfe_u32 v4, v3, 16, 1
	v_add3_u32 v3, v3, v4, s71
	ds_write_b16_d16_hi v2, v3 offset:39168
	v_fma_f32 v3, v48, v6, -v15
	v_mul_f32_e32 v3, v3, v118
	v_fma_f32 v3, v3, v63, v99
	v_bfe_u32 v4, v3, 16, 1
	v_add3_u32 v3, v3, v4, s71
	ds_write_b16_d16_hi v2, v3 offset:39440
	v_fma_f32 v3, v52, v50, -v15
	v_mul_f32_e32 v3, v3, v118
	v_fma_f32 v3, v3, v64, v100
	v_bfe_u32 v4, v3, 16, 1
	v_add3_u32 v3, v3, v4, s71
	ds_write_b16_d16_hi v2, v3 offset:39712
	v_fma_f32 v3, v51, v7, -v15
	v_mul_f32_e32 v3, v3, v118
	v_fmac_f32_e32 v101, v3, v65
	v_bfe_u32 v3, v101, 16, 1
	v_add3_u32 v3, v101, v3, s71
	ds_write_b16_d16_hi v2, v3 offset:39984
	v_fma_f32 v3, v55, v53, -v15
	v_mul_f32_e32 v3, v3, v118
	v_fma_f32 v3, v3, v58, v94
	v_bfe_u32 v4, v3, 16, 1
	v_add3_u32 v3, v3, v4, s71
	ds_write_b16_d16_hi v2, v3 offset:40256
	v_fma_f32 v3, v54, v8, -v15
	v_mul_f32_e32 v3, v3, v118
	v_fma_f32 v3, v3, v59, v95
	v_bfe_u32 v4, v3, 16, 1
	v_add3_u32 v3, v3, v4, s71
	ds_write_b16_d16_hi v2, v3 offset:40528
	v_fma_f32 v3, v69, v56, -v15
	v_mul_f32_e32 v3, v3, v118
	v_fma_f32 v3, v3, v60, v96
	v_bfe_u32 v4, v3, 16, 1
	v_add3_u32 v3, v3, v4, s71
	ds_write_b16_d16_hi v2, v3 offset:40800
	v_fma_f32 v3, v102, v9, -v15
	v_mul_f32_e32 v3, v3, v118
	v_fmac_f32_e32 v97, v3, v61
	v_bfe_u32 v3, v97, 16, 1
	v_add3_u32 v3, v97, v3, s71
	ds_write_b16_d16_hi v2, v3 offset:41072
	v_fma_f32 v3, v105, v103, -v15
	v_mul_f32_e32 v3, v3, v118
	s_waitcnt vmcnt(0)
	v_fma_f32 v3, v3, v22, v30
	v_bfe_u32 v4, v3, 16, 1
	v_add3_u32 v3, v3, v4, s71
	ds_write_b16_d16_hi v2, v3 offset:41344
	v_fma_f32 v3, v106, v104, -v15
	v_mul_f32_e32 v3, v3, v118
	v_fma_f32 v3, v3, v23, v31
	v_bfe_u32 v4, v3, 16, 1
	v_add3_u32 v3, v3, v4, s71
	ds_write_b16_d16_hi v2, v3 offset:41616
	v_fma_f32 v3, v109, v107, -v15
	v_mul_f32_e32 v3, v3, v118
	v_fma_f32 v3, v3, v24, v32
	v_bfe_u32 v4, v3, 16, 1
	v_add3_u32 v3, v3, v4, s71
	ds_write_b16_d16_hi v2, v3 offset:41888
	v_fma_f32 v3, v110, v108, -v15
	v_mul_f32_e32 v3, v3, v118
	v_fmac_f32_e32 v33, v3, v25
	v_bfe_u32 v3, v33, 16, 1
	v_add3_u32 v3, v33, v3, s71
	ds_write_b16_d16_hi v2, v3 offset:42160
	v_fma_f32 v3, v113, v111, -v15
	v_mul_f32_e32 v3, v3, v118
	v_fma_f32 v3, v3, v18, v26
	v_bfe_u32 v4, v3, 16, 1
	v_add3_u32 v3, v3, v4, s71
	ds_write_b16_d16_hi v2, v3 offset:42432
	v_fma_f32 v3, v114, v112, -v15
	v_mul_f32_e32 v3, v3, v118
	v_fma_f32 v3, v3, v19, v27
	v_bfe_u32 v4, v3, 16, 1
	v_add3_u32 v3, v3, v4, s71
	ds_write_b16_d16_hi v2, v3 offset:42704
	v_fma_f32 v3, v116, v57, -v15
	v_mul_f32_e32 v3, v3, v118
	v_fma_f32 v3, v3, v20, v28
	v_bfe_u32 v4, v3, 16, 1
	v_add3_u32 v3, v3, v4, s71
	ds_write_b16_d16_hi v2, v3 offset:42976
	v_fma_f32 v2, v117, v115, -v15
	v_mul_f32_e32 v2, v2, v118
	v_fmac_f32_e32 v29, v2, v21
	v_bfe_u32 v2, v29, 16, 1
	v_add3_u32 v4, v29, v2, s71
	v_or_b32_e32 v2, 31, v17
	v_mad_u64_u32 v[2:3], s[40:41], v2, s65, v[0:1]
	v_ashrrev_i32_e32 v15, 31, v14
	ds_write_b16_d16_hi v2, v4 offset:34816
	v_lshl_add_u64 v[32:33], v[14:15], 0, s[52:53]
	v_mov_b64_e32 v[2:3], s[44:45]
	v_bfe_u32 v4, v16, 4, 2
	v_mad_i64_i32 v[2:3], s[22:23], v32, s61, v[2:3]
	v_lshlrev_b32_e32 v0, 3, v4
	v_lshl_add_u64 v[2:3], v[2:3], 0, s[20:21]
	v_lshl_add_u64 v[34:35], v[2:3], 0, v[0:1]
	v_add_co_u32_e32 v2, vcc, s56, v34
	s_waitcnt lgkmcnt(0)
	s_nop 0
	v_addc_co_u32_e32 v3, vcc, 0, v35, vcc
	s_barrier
; #define LAS __attribute__((address_space(3)))
; __device__ __forceinline__ unsigned pk2(float lo, float hi) { return pg8::cvt_pk_bf16(lo, hi); }
; __device__ __forceinline__ float gelu_tanh(float x) { const float z = 0.7978845608028654f * (x + 0.044715f * x * x * x); return x * frcp(1.f + fexp2(-2.f * LOG2E * z)); }
; #define ZERO8(a) do { _Pragma("unroll") for (int t_ = 0; t_ < 8; ++t_) a[t_] = (f32x4){0.f, 0.f, 0.f, 0.f}; } while (0)
; __device__ __forceinline__ void wave_mma(f32x4 (&acc)[8], const LAS bfu* As, const LAS bfu* Bs, int m0, int fr, int fq) {
;     ...
;     for (int ks = 0; ks < 4; ++ks) { const bf16x8 a = *(const LAS bf16x8*)(As + (m0 + fr) * TS + ks * 32 + fq * 8);
; #pragma unroll
;         for (int t = 0; t < 8; ++t) { const bf16x8 b = *(const LAS bf16x8*)(Bs + (t * 16 + fr) * TS + ks * 32 + fq * 8); acc[t] = __builtin_amdgcn_mfma_f32_16x16x32_bf16(b, a, acc[t], 0, 0, 0); } }
; __device__ __forceinline__ void sgu_unit(LAS unsigned char* lds, const bfu* PROJ, const bfu* SW  , const float* ln_g, const float* ln_b, const float* sb, bfu* CAT, int s) {
;     ...
;     const int fr = lane & 15, fq = lane >> 4, m0 = wid * 16, t_ = m0 + fr; f32x4 acc[8]; ZERO8(acc);
;     wave_mma(acc, Ws, Vt, m0, fr, fq);
;     const float bias = sb[g * 128 + t_];
;     const bfu* up = PROJ + (row0 + t_) * INW + C_SU + g * 128 + 4 * fq; bfu* op = CAT + (row0 + t_) * DM + 1536 + g * 128 + 4 * fq;
; #pragma unroll
;     for (int t = 0; t < 8; ++t) { const v2u uw = *(const v2u*)(up + 16 * t);
;         v2u w; w.x = pk2(gelu_tanh(bflo(uw.x)) * (acc[t][0] + bias), gelu_tanh(bfhi(uw.x)) * (acc[t][1] + bias)); w.y = pk2(gelu_tanh(bflo(uw.y)) * (acc[t][2] + bias), gelu_tanh(bfhi(uw.y)) * (acc[t][3] + bias));
;         *(v2u*)(op + 16 * t) = w; }
	global_load_dwordx2 v[170:171], v[2:3], off offset:2560
	v_and_b32_e32 v2, 15, v16
	v_lshl_add_u32 v6, v4, 4, 0
	v_mad_u32_u24 v19, v2, s65, v6
	ds_read_b128 v[2:5], v19 offset:34816
	v_mad_u64_u32 v[38:39], s[22:23], v14, s65, v[6:7]
	ds_read_b128 v[20:23], v19 offset:34880
	ds_read_b128 v[10:13], v38
	ds_read_b128 v[6:9], v38 offset:64
	ds_read_b128 v[24:27], v19 offset:34944
	s_waitcnt lgkmcnt(2)
	v_mfma_f32_16x16x32_bf16 v[2:5], v[2:5], v[10:13], 0
	v_lshl_add_u32 v28, s34, 7, v14
	v_ashrrev_i32_e32 v29, 31, v28
	v_lshl_add_u64 v[40:41], v[28:29], 2, s[50:51]
	ds_read_b128 v[14:17], v38 offset:128
	s_waitcnt lgkmcnt(2)
	v_mfma_f32_16x16x32_bf16 v[20:23], v[20:23], v[6:9], v[2:5]
	ds_read_b128 v[28:31], v19 offset:35008
	s_nop 1
	ds_read_b128 v[2:5], v38 offset:192
	global_load_dword v18, v[40:41], off
	s_mov_b64 s[22:23], 0x2a00
	s_waitcnt lgkmcnt(2)
	v_mfma_f32_16x16x32_bf16 v[20:23], v[24:27], v[14:17], v[20:23]
	v_lshlrev_b64 v[26:27], 12, v[32:33]
	v_lshl_add_u64 v[26:27], s[46:47], 0, v[26:27]
	v_lshl_add_u64 v[26:27], v[26:27], 0, s[20:21]
	s_waitcnt lgkmcnt(0)
	v_mfma_f32_16x16x32_bf16 v[22:25], v[28:31], v[2:5], v[20:23]
	s_mov_b32 s20, 0x29600000
	s_waitcnt vmcnt(1)
	v_lshlrev_b32_e32 v28, 16, v170
	v_mul_f32_e32 v30, 0x3d372713, v28
	v_mul_f32_e32 v30, v30, v28
	v_mov_b32_e32 v31, v28
	v_and_b32_e32 v29, 0xffff0000, v170
	v_fmac_f32_e32 v31, v30, v31
	v_mul_f32_e32 v30, 0x3f4c422a, v31
	v_mul_f32_e32 v31, 0x3d372713, v29
	v_mul_f32_e32 v31, v31, v29
	v_mov_b32_e32 v32, v29
	v_fmac_f32_e32 v32, v31, v32
	v_mul_f32_e32 v30, 0xc038aa3b, v30
	v_mul_f32_e32 v31, 0x3f4c422a, v32
	v_exp_f32_e32 v30, v30
	v_mul_f32_e32 v31, 0xc038aa3b, v31
	v_exp_f32_e32 v31, v31
	v_lshl_add_u64 v[20:21], v[34:35], 0, s[22:23]
	global_load_dwordx2 v[172:173], v[20:21], off offset:32
	global_load_dwordx2 v[174:175], v[20:21], off offset:64
	global_load_dwordx2 v[176:177], v[20:21], off offset:96
	global_load_dwordx2 v[178:179], v[20:21], off offset:128
	global_load_dwordx2 v[180:181], v[20:21], off offset:160
	global_load_dwordx2 v[182:183], v[20:21], off offset:192
	global_load_dwordx2 v[184:185], v[20:21], off offset:224
	v_lshl_add_u64 v[34:35], v[26:27], 0, v[0:1]
	v_add_f32_e32 v0, 1.0, v30
	v_rcp_f32_e32 v26, v0
	v_add_f32_e32 v0, 1.0, v31
	v_lshlrev_b32_e32 v36, 16, v171
	v_rcp_f32_e32 v27, v0
	v_mul_f32_e32 v0, 0x3d372713, v36
	v_mul_f32_e32 v0, v0, v36
	v_mov_b32_e32 v30, v36
	v_and_b32_e32 v37, 0xffff0000, v171
	v_fmac_f32_e32 v30, v0, v30
	v_mul_f32_e32 v0, 0x3f4c422a, v30
	v_mul_f32_e32 v30, 0x3d372713, v37
	v_mul_f32_e32 v30, v30, v37
	v_mov_b32_e32 v31, v37
	v_fmac_f32_e32 v31, v30, v31
	v_mul_f32_e32 v0, 0xc038aa3b, v0
	v_mul_f32_e32 v30, 0x3f4c422a, v31
	v_exp_f32_e32 v0, v0
	v_mul_f32_e32 v30, 0xc038aa3b, v30
	v_exp_f32_e32 v30, v30
	v_pk_mul_f32 v[38:39], v[26:27], v[28:29]
	ds_read_b128 v[26:29], v19 offset:39168
	v_add_f32_e32 v0, 1.0, v0
	v_rcp_f32_e32 v40, v0
	v_add_f32_e32 v0, 1.0, v30
	v_rcp_f32_e32 v41, v0
	ds_read_b128 v[30:33], v19 offset:39232
	s_waitcnt vmcnt(0)
	v_pk_add_f32 v[22:23], v[22:23], v[18:19] op_sel_hi:[1,0]
	s_mov_b64 s[22:23], 0x29600c00
	v_pk_mul_f32 v[22:23], v[22:23], v[38:39]
	v_pk_mul_f32 v[36:37], v[40:41], v[36:37]
	v_cvt_pk_bf16_f32 v38, v22, v23
	v_pk_add_f32 v[40:41], v[24:25], v[18:19] op_sel_hi:[1,0]
	s_waitcnt lgkmcnt(1)
	v_mfma_f32_16x16x32_bf16 v[22:25], v[26:29], v[10:13], 0
	ds_read_b128 v[26:29], v19 offset:39296
	v_pk_mul_f32 v[36:37], v[40:41], v[36:37]
	s_waitcnt lgkmcnt(1)
	v_mfma_f32_16x16x32_bf16 v[22:25], v[30:33], v[6:9], v[22:25]
	v_add_co_u32_e32 v30, vcc, s20, v34
	v_cvt_pk_bf16_f32 v39, v36, v37
	s_nop 0
	v_addc_co_u32_e32 v31, vcc, 0, v35, vcc
	global_store_dwordx2 v[30:31], v[38:39], off offset:3072
	ds_read_b128 v[30:33], v19 offset:39360
	s_waitcnt lgkmcnt(1)
	v_mfma_f32_16x16x32_bf16 v[22:25], v[26:29], v[14:17], v[22:25]
	s_waitcnt lgkmcnt(0)
	v_mfma_f32_16x16x32_bf16 v[24:27], v[30:33], v[2:5], v[22:25]
	s_waitcnt vmcnt(0)
	v_lshlrev_b32_e32 v30, 16, v172
	v_mul_f32_e32 v0, 0x3d372713, v30
	v_mul_f32_e32 v0, v0, v30
	s_nop 0
	v_mov_b32_e32 v22, v30
	v_and_b32_e32 v31, 0xffff0000, v172
	v_fmac_f32_e32 v22, v0, v22
	v_mul_f32_e32 v0, 0x3f4c422a, v22
	v_mul_f32_e32 v22, 0x3d372713, v31
	v_mul_f32_e32 v22, v22, v31
	v_mov_b32_e32 v23, v31
	v_fmac_f32_e32 v23, v22, v23
	v_mul_f32_e32 v0, 0xc038aa3b, v0
	v_mul_f32_e32 v22, 0x3f4c422a, v23
	v_exp_f32_e32 v0, v0
	v_mul_f32_e32 v22, 0xc038aa3b, v22
	v_exp_f32_e32 v28, v22
	v_lshl_add_u64 v[22:23], v[34:35], 0, s[22:23]
	v_add_f32_e32 v0, 1.0, v0
	v_rcp_f32_e32 v32, v0
	v_add_f32_e32 v0, 1.0, v28
	v_lshlrev_b32_e32 v34, 16, v173
	v_rcp_f32_e32 v33, v0
	v_mul_f32_e32 v0, 0x3d372713, v34
	v_mul_f32_e32 v0, v0, v34
	v_mov_b32_e32 v28, v34
	v_and_b32_e32 v35, 0xffff0000, v173
	v_fmac_f32_e32 v28, v0, v28
	v_mul_f32_e32 v0, 0x3f4c422a, v28
	v_mul_f32_e32 v28, 0x3d372713, v35
	v_mul_f32_e32 v28, v28, v35
	v_mov_b32_e32 v29, v35
	v_fmac_f32_e32 v29, v28, v29
	v_mul_f32_e32 v0, 0xc038aa3b, v0
	v_mul_f32_e32 v28, 0x3f4c422a, v29
	v_exp_f32_e32 v0, v0
	v_mul_f32_e32 v28, 0xc038aa3b, v28
	v_exp_f32_e32 v28, v28
	v_pk_mul_f32 v[32:33], v[32:33], v[30:31]
	v_add_f32_e32 v0, 1.0, v0
	v_rcp_f32_e32 v36, v0
	v_add_f32_e32 v0, 1.0, v28
	v_rcp_f32_e32 v37, v0
	v_pk_add_f32 v[24:25], v[24:25], v[18:19] op_sel_hi:[1,0]
	v_pk_add_f32 v[26:27], v[26:27], v[18:19] op_sel_hi:[1,0]
	v_pk_mul_f32 v[24:25], v[24:25], v[32:33]
	v_pk_mul_f32 v[32:33], v[36:37], v[34:35]
	v_cvt_pk_bf16_f32 v24, v24, v25
	v_pk_mul_f32 v[26:27], v[26:27], v[32:33]
	ds_read_b128 v[28:31], v19 offset:43520
	v_cvt_pk_bf16_f32 v25, v26, v27
	global_store_dwordx2 v[22:23], v[24:25], off offset:32
	ds_read_b128 v[24:27], v19 offset:43584
	s_waitcnt lgkmcnt(1)
; #define LAS __attribute__((address_space(3)))
; __device__ __forceinline__ unsigned pk2(float lo, float hi) { return pg8::cvt_pk_bf16(lo, hi); }
; __device__ __forceinline__ float gelu_tanh(float x) { const float z = 0.7978845608028654f * (x + 0.044715f * x * x * x); return x * frcp(1.f + fexp2(-2.f * LOG2E * z)); }
; __device__ __forceinline__ void wave_mma(f32x4 (&acc)[8], const LAS bfu* As, const LAS bfu* Bs, int m0, int fr, int fq) {
;     ...
;     for (int ks = 0; ks < 4; ++ks) { const bf16x8 a = *(const LAS bf16x8*)(As + (m0 + fr) * TS + ks * 32 + fq * 8);
; #pragma unroll
;         for (int t = 0; t < 8; ++t) { const bf16x8 b = *(const LAS bf16x8*)(Bs + (t * 16 + fr) * TS + ks * 32 + fq * 8); acc[t] = __builtin_amdgcn_mfma_f32_16x16x32_bf16(b, a, acc[t], 0, 0, 0); } }
; __device__ __forceinline__ void sgu_unit(LAS unsigned char* lds, const bfu* PROJ, const bfu* SW  , const float* ln_g, const float* ln_b, const float* sb, bfu* CAT, int s) {
;     ...
;     for (int t = 0; t < 8; ++t) { const v2u uw = *(const v2u*)(up + 16 * t);
;         v2u w; w.x = pk2(gelu_tanh(bflo(uw.x)) * (acc[t][0] + bias), gelu_tanh(bfhi(uw.x)) * (acc[t][1] + bias)); w.y = pk2(gelu_tanh(bflo(uw.y)) * (acc[t][2] + bias), gelu_tanh(bfhi(uw.y)) * (acc[t][3] + bias));
;         *(v2u*)(op + 16 * t) = w; }
	v_mfma_f32_16x16x32_bf16 v[28:31], v[28:31], v[10:13], 0
	s_waitcnt lgkmcnt(0)
	v_mfma_f32_16x16x32_bf16 v[24:27], v[24:27], v[6:9], v[28:31]
	s_nop 5
	ds_read_b128 v[28:31], v19 offset:43648
	ds_read_b128 v[32:35], v19 offset:43712
	s_waitcnt lgkmcnt(1)
	v_mfma_f32_16x16x32_bf16 v[24:27], v[28:31], v[14:17], v[24:27]
	s_waitcnt vmcnt(0)
	v_lshlrev_b32_e32 v28, 16, v174
	v_mul_f32_e32 v0, 0x3d372713, v28
	v_mul_f32_e32 v0, v0, v28
	v_mov_b32_e32 v30, v28
	v_and_b32_e32 v29, 0xffff0000, v174
	v_fmac_f32_e32 v30, v0, v30
	v_mul_f32_e32 v0, 0x3f4c422a, v30
	v_mul_f32_e32 v30, 0x3d372713, v29
	v_mul_f32_e32 v30, v30, v29
	v_mov_b32_e32 v31, v29
	v_fmac_f32_e32 v31, v30, v31
	v_mul_f32_e32 v0, 0xc038aa3b, v0
	v_mul_f32_e32 v30, 0x3f4c422a, v31
	v_exp_f32_e32 v0, v0
	v_mul_f32_e32 v30, 0xc038aa3b, v30
	v_exp_f32_e32 v31, v30
	s_waitcnt lgkmcnt(0)
	v_mfma_f32_16x16x32_bf16 v[24:27], v[32:35], v[2:5], v[24:27]
	v_add_f32_e32 v0, 1.0, v0
	v_rcp_f32_e32 v30, v0
	v_add_f32_e32 v0, 1.0, v31
	v_lshlrev_b32_e32 v32, 16, v175
	v_rcp_f32_e32 v31, v0
	v_mul_f32_e32 v0, 0x3d372713, v32
	v_mul_f32_e32 v0, v0, v32
	v_mov_b32_e32 v34, v32
	v_and_b32_e32 v33, 0xffff0000, v175
	v_fmac_f32_e32 v34, v0, v34
	v_mul_f32_e32 v0, 0x3f4c422a, v34
	v_mul_f32_e32 v34, 0x3d372713, v33
	v_mul_f32_e32 v34, v34, v33
	v_mov_b32_e32 v35, v33
	v_fmac_f32_e32 v35, v34, v35
	v_mul_f32_e32 v0, 0xc038aa3b, v0
	v_mul_f32_e32 v34, 0x3f4c422a, v35
	v_exp_f32_e32 v0, v0
	v_mul_f32_e32 v34, 0xc038aa3b, v34
	v_exp_f32_e32 v37, v34
	v_pk_mul_f32 v[34:35], v[30:31], v[28:29]
	v_add_f32_e32 v0, 1.0, v0
	v_rcp_f32_e32 v36, v0
	v_add_f32_e32 v0, 1.0, v37
	v_rcp_f32_e32 v37, v0
	v_pk_add_f32 v[24:25], v[24:25], v[18:19] op_sel_hi:[1,0]
	v_pk_add_f32 v[26:27], v[26:27], v[18:19] op_sel_hi:[1,0]
	v_pk_mul_f32 v[24:25], v[24:25], v[34:35]
	v_pk_mul_f32 v[32:33], v[36:37], v[32:33]
	v_cvt_pk_bf16_f32 v24, v24, v25
	v_pk_mul_f32 v[26:27], v[26:27], v[32:33]
	ds_read_b128 v[28:31], v19 offset:47872
	v_cvt_pk_bf16_f32 v25, v26, v27
	global_store_dwordx2 v[22:23], v[24:25], off offset:64
	ds_read_b128 v[24:27], v19 offset:47936
	s_waitcnt lgkmcnt(1)
	v_mfma_f32_16x16x32_bf16 v[28:31], v[28:31], v[10:13], 0
	s_waitcnt lgkmcnt(0)
	v_mfma_f32_16x16x32_bf16 v[24:27], v[24:27], v[6:9], v[28:31]
	s_nop 5
	ds_read_b128 v[28:31], v19 offset:48000
	ds_read_b128 v[32:35], v19 offset:48064
	s_waitcnt lgkmcnt(1)
	v_mfma_f32_16x16x32_bf16 v[24:27], v[28:31], v[14:17], v[24:27]
	s_waitcnt vmcnt(0)
	v_lshlrev_b32_e32 v28, 16, v176
	v_mul_f32_e32 v0, 0x3d372713, v28
	v_mul_f32_e32 v0, v0, v28
	v_mov_b32_e32 v30, v28
	v_and_b32_e32 v29, 0xffff0000, v176
	v_fmac_f32_e32 v30, v0, v30
	v_mul_f32_e32 v0, 0x3f4c422a, v30
	v_mul_f32_e32 v30, 0x3d372713, v29
	v_mul_f32_e32 v30, v30, v29
	v_mov_b32_e32 v31, v29
	v_fmac_f32_e32 v31, v30, v31
	v_mul_f32_e32 v0, 0xc038aa3b, v0
	v_mul_f32_e32 v30, 0x3f4c422a, v31
	v_exp_f32_e32 v0, v0
	v_mul_f32_e32 v30, 0xc038aa3b, v30
	v_exp_f32_e32 v31, v30
	s_waitcnt lgkmcnt(0)
	v_mfma_f32_16x16x32_bf16 v[24:27], v[32:35], v[2:5], v[24:27]
	v_add_f32_e32 v0, 1.0, v0
	v_rcp_f32_e32 v30, v0
	v_add_f32_e32 v0, 1.0, v31
	v_lshlrev_b32_e32 v32, 16, v177
	v_rcp_f32_e32 v31, v0
	v_mul_f32_e32 v0, 0x3d372713, v32
	v_mul_f32_e32 v0, v0, v32
	v_mov_b32_e32 v34, v32
	v_and_b32_e32 v33, 0xffff0000, v177
	v_fmac_f32_e32 v34, v0, v34
	v_mul_f32_e32 v0, 0x3f4c422a, v34
	v_mul_f32_e32 v34, 0x3d372713, v33
	v_mul_f32_e32 v34, v34, v33
	v_mov_b32_e32 v35, v33
	v_fmac_f32_e32 v35, v34, v35
	v_mul_f32_e32 v0, 0xc038aa3b, v0
	v_mul_f32_e32 v34, 0x3f4c422a, v35
	v_exp_f32_e32 v0, v0
	v_mul_f32_e32 v34, 0xc038aa3b, v34
	v_exp_f32_e32 v37, v34
	v_pk_mul_f32 v[34:35], v[30:31], v[28:29]
	v_add_f32_e32 v0, 1.0, v0
	v_rcp_f32_e32 v36, v0
	v_add_f32_e32 v0, 1.0, v37
	v_rcp_f32_e32 v37, v0
	v_pk_add_f32 v[24:25], v[24:25], v[18:19] op_sel_hi:[1,0]
	v_pk_add_f32 v[26:27], v[26:27], v[18:19] op_sel_hi:[1,0]
	v_pk_mul_f32 v[24:25], v[24:25], v[34:35]
	v_pk_mul_f32 v[32:33], v[36:37], v[32:33]
	v_cvt_pk_bf16_f32 v24, v24, v25
	v_pk_mul_f32 v[26:27], v[26:27], v[32:33]
	ds_read_b128 v[28:31], v19 offset:52224
	v_cvt_pk_bf16_f32 v25, v26, v27
	global_store_dwordx2 v[22:23], v[24:25], off offset:96
	ds_read_b128 v[24:27], v19 offset:52288
	s_waitcnt lgkmcnt(1)
	v_mfma_f32_16x16x32_bf16 v[28:31], v[28:31], v[10:13], 0
	s_waitcnt lgkmcnt(0)
	v_mfma_f32_16x16x32_bf16 v[24:27], v[24:27], v[6:9], v[28:31]
	s_nop 5
	ds_read_b128 v[28:31], v19 offset:52352
	ds_read_b128 v[32:35], v19 offset:52416
	s_waitcnt lgkmcnt(1)
	v_mfma_f32_16x16x32_bf16 v[24:27], v[28:31], v[14:17], v[24:27]
	s_waitcnt vmcnt(0)
	v_lshlrev_b32_e32 v28, 16, v178
	v_mul_f32_e32 v0, 0x3d372713, v28
	v_mul_f32_e32 v0, v0, v28
	v_mov_b32_e32 v30, v28
	v_and_b32_e32 v29, 0xffff0000, v178
	v_fmac_f32_e32 v30, v0, v30
	v_mul_f32_e32 v0, 0x3f4c422a, v30
	v_mul_f32_e32 v30, 0x3d372713, v29
	v_mul_f32_e32 v30, v30, v29
	v_mov_b32_e32 v31, v29
	v_fmac_f32_e32 v31, v30, v31
	v_mul_f32_e32 v0, 0xc038aa3b, v0
	v_mul_f32_e32 v30, 0x3f4c422a, v31
	v_exp_f32_e32 v0, v0
	v_mul_f32_e32 v30, 0xc038aa3b, v30
	v_exp_f32_e32 v31, v30
	s_waitcnt lgkmcnt(0)
; #define LAS __attribute__((address_space(3)))
; __device__ __forceinline__ unsigned pk2(float lo, float hi) { return pg8::cvt_pk_bf16(lo, hi); }
; __device__ __forceinline__ float gelu_tanh(float x) { const float z = 0.7978845608028654f * (x + 0.044715f * x * x * x); return x * frcp(1.f + fexp2(-2.f * LOG2E * z)); }
; __device__ __forceinline__ void wave_mma(f32x4 (&acc)[8], const LAS bfu* As, const LAS bfu* Bs, int m0, int fr, int fq) {
;     ...
;     for (int ks = 0; ks < 4; ++ks) { const bf16x8 a = *(const LAS bf16x8*)(As + (m0 + fr) * TS + ks * 32 + fq * 8);
; #pragma unroll
;         for (int t = 0; t < 8; ++t) { const bf16x8 b = *(const LAS bf16x8*)(Bs + (t * 16 + fr) * TS + ks * 32 + fq * 8); acc[t] = __builtin_amdgcn_mfma_f32_16x16x32_bf16(b, a, acc[t], 0, 0, 0); } }
; __device__ __forceinline__ void sgu_unit(LAS unsigned char* lds, const bfu* PROJ, const bfu* SW  , const float* ln_g, const float* ln_b, const float* sb, bfu* CAT, int s) {
;     ...
;     for (int t = 0; t < 8; ++t) { const v2u uw = *(const v2u*)(up + 16 * t);
;         v2u w; w.x = pk2(gelu_tanh(bflo(uw.x)) * (acc[t][0] + bias), gelu_tanh(bfhi(uw.x)) * (acc[t][1] + bias)); w.y = pk2(gelu_tanh(bflo(uw.y)) * (acc[t][2] + bias), gelu_tanh(bfhi(uw.y)) * (acc[t][3] + bias));
;         *(v2u*)(op + 16 * t) = w; }
	v_mfma_f32_16x16x32_bf16 v[24:27], v[32:35], v[2:5], v[24:27]
	v_add_f32_e32 v0, 1.0, v0
	v_rcp_f32_e32 v30, v0
	v_add_f32_e32 v0, 1.0, v31
	v_lshlrev_b32_e32 v32, 16, v179
	v_rcp_f32_e32 v31, v0
	v_mul_f32_e32 v0, 0x3d372713, v32
	v_mul_f32_e32 v0, v0, v32
	v_mov_b32_e32 v34, v32
	v_and_b32_e32 v33, 0xffff0000, v179
	v_fmac_f32_e32 v34, v0, v34
	v_mul_f32_e32 v0, 0x3f4c422a, v34
	v_mul_f32_e32 v34, 0x3d372713, v33
	v_mul_f32_e32 v34, v34, v33
	v_mov_b32_e32 v35, v33
	v_fmac_f32_e32 v35, v34, v35
	v_mul_f32_e32 v0, 0xc038aa3b, v0
	v_mul_f32_e32 v34, 0x3f4c422a, v35
	v_exp_f32_e32 v0, v0
	v_mul_f32_e32 v34, 0xc038aa3b, v34
	v_exp_f32_e32 v37, v34
	v_pk_mul_f32 v[34:35], v[30:31], v[28:29]
	v_add_f32_e32 v0, 1.0, v0
	v_rcp_f32_e32 v36, v0
	v_add_f32_e32 v0, 1.0, v37
	v_rcp_f32_e32 v37, v0
	v_pk_add_f32 v[24:25], v[24:25], v[18:19] op_sel_hi:[1,0]
	v_pk_add_f32 v[26:27], v[26:27], v[18:19] op_sel_hi:[1,0]
	v_pk_mul_f32 v[24:25], v[24:25], v[34:35]
	v_pk_mul_f32 v[32:33], v[36:37], v[32:33]
	v_cvt_pk_bf16_f32 v24, v24, v25
	v_pk_mul_f32 v[26:27], v[26:27], v[32:33]
	ds_read_b128 v[28:31], v19 offset:56576
	v_cvt_pk_bf16_f32 v25, v26, v27
	global_store_dwordx2 v[22:23], v[24:25], off offset:128
	ds_read_b128 v[24:27], v19 offset:56640
	s_waitcnt lgkmcnt(1)
	v_mfma_f32_16x16x32_bf16 v[28:31], v[28:31], v[10:13], 0
	s_waitcnt lgkmcnt(0)
	v_mfma_f32_16x16x32_bf16 v[24:27], v[24:27], v[6:9], v[28:31]
	s_nop 5
	ds_read_b128 v[28:31], v19 offset:56704
	ds_read_b128 v[32:35], v19 offset:56768
	s_waitcnt lgkmcnt(1)
	v_mfma_f32_16x16x32_bf16 v[24:27], v[28:31], v[14:17], v[24:27]
	s_waitcnt vmcnt(0)
	v_lshlrev_b32_e32 v28, 16, v180
	v_mul_f32_e32 v0, 0x3d372713, v28
	v_mul_f32_e32 v0, v0, v28
	v_mov_b32_e32 v30, v28
	v_and_b32_e32 v29, 0xffff0000, v180
	v_fmac_f32_e32 v30, v0, v30
	v_mul_f32_e32 v0, 0x3f4c422a, v30
	v_mul_f32_e32 v30, 0x3d372713, v29
	v_mul_f32_e32 v30, v30, v29
	v_mov_b32_e32 v31, v29
	v_fmac_f32_e32 v31, v30, v31
	v_mul_f32_e32 v0, 0xc038aa3b, v0
	v_mul_f32_e32 v30, 0x3f4c422a, v31
	v_exp_f32_e32 v0, v0
	v_mul_f32_e32 v30, 0xc038aa3b, v30
	v_exp_f32_e32 v31, v30
	s_waitcnt lgkmcnt(0)
	v_mfma_f32_16x16x32_bf16 v[24:27], v[32:35], v[2:5], v[24:27]
	v_add_f32_e32 v0, 1.0, v0
	v_rcp_f32_e32 v30, v0
	v_add_f32_e32 v0, 1.0, v31
	v_lshlrev_b32_e32 v32, 16, v181
	v_rcp_f32_e32 v31, v0
	v_mul_f32_e32 v0, 0x3d372713, v32
	v_mul_f32_e32 v0, v0, v32
	v_mov_b32_e32 v34, v32
	v_and_b32_e32 v33, 0xffff0000, v181
	v_fmac_f32_e32 v34, v0, v34
	v_mul_f32_e32 v0, 0x3f4c422a, v34
	v_mul_f32_e32 v34, 0x3d372713, v33
	v_mul_f32_e32 v34, v34, v33
	v_mov_b32_e32 v35, v33
	v_fmac_f32_e32 v35, v34, v35
	v_mul_f32_e32 v0, 0xc038aa3b, v0
	v_mul_f32_e32 v34, 0x3f4c422a, v35
	v_exp_f32_e32 v0, v0
	v_mul_f32_e32 v34, 0xc038aa3b, v34
	v_exp_f32_e32 v37, v34
	v_pk_mul_f32 v[34:35], v[30:31], v[28:29]
	v_add_f32_e32 v0, 1.0, v0
	v_rcp_f32_e32 v36, v0
	v_add_f32_e32 v0, 1.0, v37
	v_rcp_f32_e32 v37, v0
	v_pk_add_f32 v[24:25], v[24:25], v[18:19] op_sel_hi:[1,0]
	v_pk_add_f32 v[26:27], v[26:27], v[18:19] op_sel_hi:[1,0]
	v_pk_mul_f32 v[24:25], v[24:25], v[34:35]
	v_pk_mul_f32 v[32:33], v[36:37], v[32:33]
	v_cvt_pk_bf16_f32 v24, v24, v25
	v_pk_mul_f32 v[26:27], v[26:27], v[32:33]
	ds_read_b128 v[28:31], v19 offset:60928
	v_cvt_pk_bf16_f32 v25, v26, v27
	global_store_dwordx2 v[22:23], v[24:25], off offset:160
	ds_read_b128 v[24:27], v19 offset:60992
	s_waitcnt lgkmcnt(1)
	v_mfma_f32_16x16x32_bf16 v[28:31], v[28:31], v[10:13], 0
	s_waitcnt lgkmcnt(0)
	v_mfma_f32_16x16x32_bf16 v[24:27], v[24:27], v[6:9], v[28:31]
	s_nop 5
	ds_read_b128 v[28:31], v19 offset:61056
	ds_read_b128 v[32:35], v19 offset:61120
	s_waitcnt lgkmcnt(1)
	v_mfma_f32_16x16x32_bf16 v[24:27], v[28:31], v[14:17], v[24:27]
	s_waitcnt vmcnt(0)
; #define LAS __attribute__((address_space(3)))
; __device__ __forceinline__ unsigned pk2(float lo, float hi) { return pg8::cvt_pk_bf16(lo, hi); }
; __device__ __forceinline__ float gelu_tanh(float x) { const float z = 0.7978845608028654f * (x + 0.044715f * x * x * x); return x * frcp(1.f + fexp2(-2.f * LOG2E * z)); }
; __device__ __forceinline__ void wave_mma(f32x4 (&acc)[8], const LAS bfu* As, const LAS bfu* Bs, int m0, int fr, int fq) {
;     ...
;     for (int ks = 0; ks < 4; ++ks) { const bf16x8 a = *(const LAS bf16x8*)(As + (m0 + fr) * TS + ks * 32 + fq * 8);
; #pragma unroll
;         for (int t = 0; t < 8; ++t) { const bf16x8 b = *(const LAS bf16x8*)(Bs + (t * 16 + fr) * TS + ks * 32 + fq * 8); acc[t] = __builtin_amdgcn_mfma_f32_16x16x32_bf16(b, a, acc[t], 0, 0, 0); } }
; __device__ __forceinline__ void sgu_unit(LAS unsigned char* lds, const bfu* PROJ, const bfu* SW  , const float* ln_g, const float* ln_b, const float* sb, bfu* CAT, int s) {
;     ...
;     wave_mma(acc, Ws, Vt, m0, fr, fq);
;     const float bias = sb[g * 128 + t_];
;     const bfu* up = PROJ + (row0 + t_) * INW + C_SU + g * 128 + 4 * fq; bfu* op = CAT + (row0 + t_) * DM + 1536 + g * 128 + 4 * fq;
; #pragma unroll
;     for (int t = 0; t < 8; ++t) { const v2u uw = *(const v2u*)(up + 16 * t);
;         v2u w; w.x = pk2(gelu_tanh(bflo(uw.x)) * (acc[t][0] + bias), gelu_tanh(bfhi(uw.x)) * (acc[t][1] + bias)); w.y = pk2(gelu_tanh(bflo(uw.y)) * (acc[t][2] + bias), gelu_tanh(bfhi(uw.y)) * (acc[t][3] + bias));
;         *(v2u*)(op + 16 * t) = w; }
	v_lshlrev_b32_e32 v28, 16, v182
	v_mul_f32_e32 v0, 0x3d372713, v28
	v_mul_f32_e32 v0, v0, v28
	v_mov_b32_e32 v30, v28
	v_and_b32_e32 v29, 0xffff0000, v182
	v_fmac_f32_e32 v30, v0, v30
	v_mul_f32_e32 v0, 0x3f4c422a, v30
	v_mul_f32_e32 v30, 0x3d372713, v29
	v_mul_f32_e32 v30, v30, v29
	v_mov_b32_e32 v31, v29
	v_fmac_f32_e32 v31, v30, v31
	v_mul_f32_e32 v0, 0xc038aa3b, v0
	v_mul_f32_e32 v30, 0x3f4c422a, v31
	v_exp_f32_e32 v0, v0
	v_mul_f32_e32 v30, 0xc038aa3b, v30
	v_exp_f32_e32 v31, v30
	s_waitcnt lgkmcnt(0)
	v_mfma_f32_16x16x32_bf16 v[24:27], v[32:35], v[2:5], v[24:27]
	v_add_f32_e32 v0, 1.0, v0
	v_rcp_f32_e32 v30, v0
	v_add_f32_e32 v0, 1.0, v31
	v_lshlrev_b32_e32 v32, 16, v183
	v_rcp_f32_e32 v31, v0
	v_mul_f32_e32 v0, 0x3d372713, v32
	v_mul_f32_e32 v0, v0, v32
	v_mov_b32_e32 v34, v32
	v_and_b32_e32 v33, 0xffff0000, v183
	v_fmac_f32_e32 v34, v0, v34
	v_mul_f32_e32 v0, 0x3f4c422a, v34
	v_mul_f32_e32 v34, 0x3d372713, v33
	v_mul_f32_e32 v34, v34, v33
	v_mov_b32_e32 v35, v33
	v_fmac_f32_e32 v35, v34, v35
	v_mul_f32_e32 v0, 0xc038aa3b, v0
	v_mul_f32_e32 v34, 0x3f4c422a, v35
	v_exp_f32_e32 v0, v0
	v_mul_f32_e32 v34, 0xc038aa3b, v34
	v_exp_f32_e32 v37, v34
	v_pk_mul_f32 v[34:35], v[30:31], v[28:29]
	v_add_f32_e32 v0, 1.0, v0
	v_rcp_f32_e32 v36, v0
	v_add_f32_e32 v0, 1.0, v37
	v_rcp_f32_e32 v37, v0
	v_pk_add_f32 v[24:25], v[24:25], v[18:19] op_sel_hi:[1,0]
	v_pk_add_f32 v[26:27], v[26:27], v[18:19] op_sel_hi:[1,0]
	v_pk_mul_f32 v[24:25], v[24:25], v[34:35]
	v_pk_mul_f32 v[32:33], v[36:37], v[32:33]
	v_cvt_pk_bf16_f32 v24, v24, v25
	v_pk_mul_f32 v[26:27], v[26:27], v[32:33]
	ds_read_b128 v[28:31], v19 offset:65280
	v_cvt_pk_bf16_f32 v25, v26, v27
	global_store_dwordx2 v[22:23], v[24:25], off offset:192
	ds_read_b128 v[24:27], v19 offset:65344
	s_waitcnt lgkmcnt(1)
	v_mfma_f32_16x16x32_bf16 v[10:13], v[28:31], v[10:13], 0
	s_waitcnt lgkmcnt(0)
	v_mfma_f32_16x16x32_bf16 v[6:9], v[24:27], v[6:9], v[10:13]
	s_nop 5
	ds_read_b128 v[10:13], v19 offset:65408
	ds_read_b128 v[24:27], v19 offset:65472
	s_waitcnt lgkmcnt(1)
	v_mfma_f32_16x16x32_bf16 v[6:9], v[10:13], v[14:17], v[6:9]
	s_waitcnt vmcnt(0)
	v_lshlrev_b32_e32 v10, 16, v184
	v_mul_f32_e32 v0, 0x3d372713, v10
	v_mul_f32_e32 v0, v0, v10
	v_mov_b32_e32 v12, v10
	v_and_b32_e32 v11, 0xffff0000, v184
	v_fmac_f32_e32 v12, v0, v12
	v_mul_f32_e32 v0, 0x3f4c422a, v12
	v_mul_f32_e32 v12, 0x3d372713, v11
	v_mul_f32_e32 v12, v12, v11
	v_mov_b32_e32 v13, v11
	v_fmac_f32_e32 v13, v12, v13
	v_mul_f32_e32 v0, 0xc038aa3b, v0
	v_mul_f32_e32 v12, 0x3f4c422a, v13
	v_exp_f32_e32 v0, v0
	v_mul_f32_e32 v12, 0xc038aa3b, v12
	v_exp_f32_e32 v12, v12
	s_waitcnt lgkmcnt(0)
	v_mfma_f32_16x16x32_bf16 v[2:5], v[24:27], v[2:5], v[6:9]
	v_add_f32_e32 v0, 1.0, v0
	s_nop 1
	v_rcp_f32_e32 v6, v0
	v_add_f32_e32 v0, 1.0, v12
	v_lshlrev_b32_e32 v8, 16, v185
	v_rcp_f32_e32 v7, v0
	v_mul_f32_e32 v0, 0x3d372713, v8
	v_mul_f32_e32 v0, v0, v8
	v_mov_b32_e32 v12, v8
	v_and_b32_e32 v9, 0xffff0000, v185
	v_fmac_f32_e32 v12, v0, v12
	v_mul_f32_e32 v0, 0x3f4c422a, v12
	v_mul_f32_e32 v12, 0x3d372713, v9
	v_mul_f32_e32 v12, v12, v9
	v_mov_b32_e32 v13, v9
	v_fmac_f32_e32 v13, v12, v13
	v_mul_f32_e32 v0, 0xc038aa3b, v0
	v_mul_f32_e32 v12, 0x3f4c422a, v13
	v_exp_f32_e32 v0, v0
	v_mul_f32_e32 v12, 0xc038aa3b, v12
	v_exp_f32_e32 v12, v12
	v_pk_mul_f32 v[6:7], v[6:7], v[10:11]
	v_add_f32_e32 v0, 1.0, v0
	v_rcp_f32_e32 v10, v0
	v_add_f32_e32 v0, 1.0, v12
	v_rcp_f32_e32 v11, v0
	v_pk_add_f32 v[2:3], v[18:19], v[2:3] op_sel_hi:[0,1]
	v_pk_mul_f32 v[2:3], v[2:3], v[6:7]
	v_pk_add_f32 v[4:5], v[18:19], v[4:5] op_sel_hi:[0,1]
	v_pk_mul_f32 v[6:7], v[10:11], v[8:9]
	v_cvt_pk_bf16_f32 v2, v2, v3
	v_pk_mul_f32 v[4:5], v[4:5], v[6:7]
	s_nop 0
	v_cvt_pk_bf16_f32 v3, v4, v5
	global_store_dwordx2 v[22:23], v[2:3], off offset:224
	s_barrier
	s_cbranch_execnz .LBB0_411
